# DA ping-pong + next-tile K fragments prefetched before the tile barrier (lagging half issues its K DMA two tiles ahead), split before cvt_pk, PV ring of 4
# baseline (speedup 1.0000x reference)
; __device__ __forceinline__ int v_rd_base(int lane) { return ((lane & 3) << 3) | (((lane >> 2) & 3) << 6) | (((lane >> 4) & 1) << 5) | (((lane >> 5) & 1) << 8); }
; #define DPUB() do { asm volatile("s_waitcnt vmcnt(0)" ::: "memory"); __syncthreads(); } while (0)
; __device__ __forceinline__ void unit_body_da(const Unit& U, char* lds) {
;   int tid = threadIdx.x; asm volatile("" : "+v"(tid)); const int wid = __builtin_amdgcn_readfirstlane(tid >> 6), lane = tid & 63, r32 = lane & 31, hi = lane >> 5;
;   char* V_lds = lds; char* K_lds = lds + 2 * DA_VB;
;   float* ws = (float*)(lds + DA_WS_OFF) + wid * 64; float* li_l = ws; float* al_l = ws + 32;
;   float m_reg = -1e30f, l_reg = 0; f32x16 o[8] = {}; bf16x8 qr[8];
;   const bf16_t* Qw = U.Q + (long)(wid * QBLK + r32) * LDP + hi * 8;
; #pragma unroll
;   for (int d0 = 0; d0 < 8; ++d0) qr[d0] = ld8(Qw + d0 * 16);
;   const int vb0 = (int)(uintptr_t)V_lds + v_rd_base(lane);
;   const int ka0 = (int)(uintptr_t)K_lds + KSWZ(r32, hi * 16);
;   constexpr float C = SCALE * 1.4426950408889634f;
;   unsigned koff[2], voff[2][2];
; #pragma unroll
;   for (int i = 0; i < 2; ++i) { const int ob = (2 * wid + i) * 1024 + lane * 16;
;     { const int row = ob >> 8, cpos = (ob >> 4) & 15, c = cpos ^ (row & 7); koff[i] = (unsigned)(row * LDP + c * 8); }
;     { const int st = ob >> 9, kk = (st >> 2) * 8 + ((ob >> 6) & 7), c = (st & 3) * 32 + ((ob >> 1) & 31), k = (kk & ~0xC) | ((kk & 4) << 1) | ((kk & 8) >> 1);
;       voff[0][i] = (unsigned)(k * LDP + c); voff[1][i] = (unsigned)(k * LDP + 128 + c); } }
;   typedef __attribute__((address_space(3))) unsigned lds_u32;
;     ...
;   const int NT = U.nt;
;   DDMA(0, 0); DPUB();
.LBB0_426:
	s_cbranch_execz .LBB0_370
	v_mov_b32_e32 v8, v210
	v_mov_b64_e32 v[2:3], s[58:59]
	v_readfirstlane_b32 s3, v8
	s_ashr_i32 s6, s3, 6
	s_and_b32 s3, s3, 0x3fffffc0
	s_lshl_b32 s3, s3, 2
	v_and_b32_e32 v234, 31, v8
	s_add_i32 s24, s3, 0
	s_lshl_b32 s64, s6, 5
	v_bfe_u32 v233, v8, 5, 1
	s_add_i32 s24, s24, 0x18000
	v_or_b32_e32 v0, s64, v234
	s_add_i32 s67, 0, 0x10000
	v_mad_i64_i32 v[2:3], s[4:5], v0, s96, v[2:3]
	v_lshlrev_b32_e32 v212, 4, v233
	v_mov_b32_e32 v213, v1
	s_cmp_lg_u32 s67, -1
	v_lshl_add_u64 v[2:3], v[2:3], 0, v[212:213]
	s_cselect_b32 s3, s67, 0
	s_lshl_b32 s25, s6, 11
	global_load_dwordx4 v[162:165], v[2:3], off
	global_load_dwordx4 v[166:169], v[2:3], off offset:32
	global_load_dwordx4 v[170:173], v[2:3], off offset:64
	global_load_dwordx4 v[174:177], v[2:3], off offset:96
	global_load_dwordx4 v[178:181], v[2:3], off offset:128
	global_load_dwordx4 v[182:185], v[2:3], off offset:160
	global_load_dwordx4 v[186:189], v[2:3], off offset:192
	global_load_dwordx4 v[190:193], v[2:3], off offset:224
	s_ashr_i32 s4, s25, 8
	v_lshrrev_b32_e32 v2, 1, v8
	v_and_b32_e32 v9, 63, v8
	v_bfe_u32 v0, v8, 2, 2
	s_and_b32 s5, s4, 0xfffff0
	v_and_b32_e32 v2, 8, v2
	v_lshlrev_b32_e32 v12, 4, v9
	s_lshr_b32 s4, s4, 1
	v_or3_b32 v0, v2, v0, s5
	v_and_or_b32 v0, s4, 4, v0
	v_or_b32_e32 v5, 0x400, v12
	v_mul_i32_i24_e32 v13, 0x1800, v0
	v_or_b32_e32 v0, s25, v12
	v_or_b32_e32 v4, s25, v5
	v_and_b32_e32 v3, 15, v8
	v_ashrrev_i32_e32 v0, 8, v0
	v_ashrrev_i32_e32 v4, 8, v4
	v_bitop3_b32 v2, v0, v3, 15 bitop3:0x6c
	v_bitop3_b32 v3, v4, v3, 15 bitop3:0x6c
	v_mul_i32_i24_e32 v4, 0x1800, v4
	v_lshlrev_b32_e32 v10, 3, v9
	v_mul_i32_i24_e32 v0, 0x1800, v0
	v_lshl_or_b32 v4, v3, 3, v4
	v_lshrrev_b32_e32 v3, 4, v5
	v_and_b32_e32 v11, 24, v10
	v_lshl_or_b32 v0, v2, 3, v0
	v_and_b32_e32 v14, 32, v8
	v_and_b32_e32 v3, 0x60, v3
	s_add_i32 s28, s67, s25
	v_or3_b32 v2, v11, v14, v13
	v_or3_b32 v6, v11, v3, v13
	v_lshl_add_u64 v[214:215], v[0:1], 1, s[46:47]
	s_mov_b32 m0, s28
	v_mov_b32_e32 v3, v1
	s_add_i32 s29, s25, 0
	global_load_lds_dwordx4 v[214:215], off
	v_lshl_add_u64 v[2:3], v[2:3], 1, s[22:23]
	s_mov_b32 m0, s29
	s_mov_b64 s[4:5], 0x100
	s_add_i32 s65, s29, 0x4000
	s_or_b32 s66, s25, 0x400
	global_load_lds_dwordx4 v[2:3], off
	v_lshl_add_u64 v[2:3], v[2:3], 0, s[4:5]
	s_mov_b32 m0, s65
	v_mov_b32_e32 v5, v1
	s_add_i32 s67, s67, s66
	global_load_lds_dwordx4 v[2:3], off
	v_lshl_add_u64 v[216:217], v[4:5], 1, s[46:47]
	s_mov_b32 m0, s67
	v_mov_b32_e32 v7, v1
	s_add_i32 s68, s29, 0x400
	global_load_lds_dwordx4 v[216:217], off
	v_lshl_add_u64 v[2:3], v[6:7], 1, s[22:23]
	s_mov_b32 m0, s68
	s_add_i32 s69, s29, 0x4400
	global_load_lds_dwordx4 v[2:3], off
	v_lshl_add_u64 v[2:3], v[2:3], 0, s[4:5]
	s_mov_b32 m0, s69
	v_lshlrev_b32_e32 v0, 1, v8
	global_load_lds_dwordx4 v[2:3], off
	v_and_b32_e32 v0, 32, v0
	v_and_or_b32 v0, v12, s97, v0
	v_and_b32_e32 v2, 0x100, v10
	s_cmp_lg_u32 0, -1
	v_or3_b32 v0, v0, v2, v11
	v_bitop3_b32 v3, v233, v8, 15 bitop3:0x78
	s_cselect_b32 s6, 0, 0
	v_lshlrev_b32_e32 v2, 8, v234
	v_lshlrev_b32_e32 v3, 4, v3
	v_add_u32_e32 v213, s6, v0
	s_add_i32 s6, s6, 0x8000
	v_add3_u32 v235, v2, s3, v3
	v_add_u32_e32 v244, s6, v0
	v_or3_b32 v0, v13, v14, v11
	s_movk_i32 s3, 0x60
	v_lshl_add_u64 v[218:219], v[0:1], 1, s[22:23]
	v_bitop3_b32 v0, v9, s3, 64 bitop3:0xc8
	v_or3_b32 v0, v13, v0, v11
	v_mov_b32_e32 v14, v1
	v_mov_b32_e32 v15, v1
	s_waitcnt vmcnt(0)
	v_cmp_gt_u32_e64 s[4:5], 32, v9
	v_lshl_add_u64 v[220:221], v[0:1], 1, s[22:23]
	v_mov_b32_e32 v0, v1
	v_mov_b32_e32 v2, v1
	v_mov_b32_e32 v3, v1
	v_mov_b32_e32 v4, v1
	v_mov_b32_e32 v6, v1
	v_mov_b32_e32 v8, v1
	v_mov_b32_e32 v9, v1
	v_mov_b32_e32 v10, v1
	v_mov_b32_e32 v11, v1
	v_mov_b32_e32 v12, v1
	v_mov_b32_e32 v13, v1
	v_mov_b64_e32 v[128:129], v[14:15]
	v_mov_b64_e32 v[112:113], v[14:15]
	v_mov_b64_e32 v[96:97], v[14:15]
	v_mov_b64_e32 v[80:81], v[14:15]
	v_mov_b64_e32 v[64:65], v[14:15]
	v_mov_b64_e32 v[48:49], v[14:15]
	v_mov_b64_e32 v[32:33], v[14:15]
	v_mov_b64_e32 v[126:127], v[12:13]
	v_mov_b64_e32 v[124:125], v[10:11]
	v_mov_b64_e32 v[122:123], v[8:9]
	v_mov_b64_e32 v[120:121], v[6:7]
	v_mov_b64_e32 v[118:119], v[4:5]
	v_mov_b64_e32 v[116:117], v[2:3]
	v_mov_b64_e32 v[114:115], v[0:1]
	v_mov_b64_e32 v[110:111], v[12:13]
	v_mov_b64_e32 v[108:109], v[10:11]
	v_mov_b64_e32 v[106:107], v[8:9]
	v_mov_b64_e32 v[104:105], v[6:7]
	v_mov_b64_e32 v[102:103], v[4:5]
	v_mov_b64_e32 v[100:101], v[2:3]
	v_mov_b64_e32 v[98:99], v[0:1]
	v_mov_b64_e32 v[94:95], v[12:13]
	v_mov_b64_e32 v[92:93], v[10:11]
	v_mov_b64_e32 v[90:91], v[8:9]
	v_mov_b64_e32 v[88:89], v[6:7]
	v_mov_b64_e32 v[86:87], v[4:5]
	v_mov_b64_e32 v[84:85], v[2:3]
	v_mov_b64_e32 v[82:83], v[0:1]
	v_mov_b64_e32 v[78:79], v[12:13]
	v_mov_b64_e32 v[76:77], v[10:11]
	v_mov_b64_e32 v[74:75], v[8:9]
	v_mov_b64_e32 v[72:73], v[6:7]
	v_mov_b64_e32 v[70:71], v[4:5]
	v_mov_b64_e32 v[68:69], v[2:3]
	v_mov_b64_e32 v[66:67], v[0:1]
	v_mov_b64_e32 v[62:63], v[12:13]
	v_mov_b64_e32 v[60:61], v[10:11]
	v_mov_b64_e32 v[58:59], v[8:9]
	v_mov_b64_e32 v[56:57], v[6:7]
	v_mov_b64_e32 v[54:55], v[4:5]
	v_mov_b64_e32 v[52:53], v[2:3]
	v_mov_b64_e32 v[50:51], v[0:1]
	v_mov_b64_e32 v[46:47], v[12:13]
	v_mov_b64_e32 v[44:45], v[10:11]
	v_mov_b64_e32 v[42:43], v[8:9]
	v_mov_b64_e32 v[40:41], v[6:7]
	v_mov_b64_e32 v[38:39], v[4:5]
	v_mov_b64_e32 v[36:37], v[2:3]
	v_mov_b64_e32 v[34:35], v[0:1]
	v_mov_b64_e32 v[30:31], v[12:13]
	v_mov_b64_e32 v[28:29], v[10:11]
	v_mov_b64_e32 v[26:27], v[8:9]
	v_mov_b64_e32 v[24:25], v[6:7]
	v_mov_b64_e32 v[22:23], v[4:5]
	v_mov_b64_e32 v[20:21], v[2:3]
	v_mov_b64_e32 v[18:19], v[0:1]
	v_mov_b64_e32 v[16:17], v[14:15]
	s_mov_b32 s80, 2
	v_xor_b32_e32 v236, 32, v235
	v_xor_b32_e32 v238, 64, v235
	v_xor_b32_e32 v239, 0x60, v235
	v_xor_b32_e32 v240, 0x80, v235
	v_xor_b32_e32 v241, 0xa0, v235
	v_xor_b32_e32 v242, 0xc0, v235
	v_xor_b32_e32 v243, 0xe0, v235
	v_lshl_add_u32 v237, v234, 2, s24
	v_mov_b32_e32 v245, 0
	v_mov_b32_e32 v246, 0xf149f2ca
	s_mov_b64 s[22:23], 0
	v_mov_b64_e32 v[14:15], v[12:13]
	v_mov_b64_e32 v[12:13], v[10:11]
	v_mov_b64_e32 v[10:11], v[8:9]
	v_mov_b64_e32 v[8:9], v[6:7]
	v_mov_b64_e32 v[6:7], v[4:5]
	v_mov_b64_e32 v[4:5], v[2:3]
	v_mov_b64_e32 v[2:3], v[0:1]
	s_waitcnt vmcnt(0) lgkmcnt(0)
	s_barrier
	ds_read_b128 v[194:197], v235 offset:0
	ds_read_b128 v[198:201], v236 offset:0
	ds_read_b128 v[202:205], v238 offset:0
	ds_read_b128 v[206:209], v239 offset:0
	s_cmp_lt_u32 s25, 0x2000
	s_cbranch_scc1 .Lda_l0_lead_in
	v_lshl_add_u64 v[232:233], v[214:215], 0, s[10:11]
	s_add_i32 m0, s62, s25
	s_nop 0
	global_load_lds_dwordx4 v[232:233], off
	v_lshl_add_u64 v[232:233], v[216:217], 0, s[10:11]
	s_add_i32 m0, s62, s66
	s_nop 0
	global_load_lds_dwordx4 v[232:233], off
	s_barrier

; #define SBAR() __builtin_amdgcn_sched_barrier(0)
; __device__ __forceinline__ void partialSM(f32x16& p0, f32x16& p1, float& m_reg, float& mn, float& alpha) {
;     ...
;   float mnC = -mn * C;
; #pragma unroll
;   for (int r = 0; r < 16; ++r) p0[r] = fmaf(p0[r], C, mnC);
; #pragma unroll
;   for (int r = 0; r < 16; ++r) p1[r] = fmaf(p1[r], C, mnC);
; #pragma unroll
;   for (int r = 0; r < 16; ++r) p0[r] = __builtin_amdgcn_exp2f(p0[r]);
; }
; __device__ __forceinline__ void finishSM(f32x16& p0, f32x16& p1, float alpha, float& l_reg, bf16x8& pa0, bf16x8& pa1, bf16x8& pa2, bf16x8& pa3) {
; #pragma unroll
;   for (int r = 0; r < 16; ++r) p1[r] = __builtin_amdgcn_exp2f(p1[r]);
;   float ps = 0;
; #pragma unroll
;   for (int r = 0; r < 16; ++r) ps += p0[r];
; #pragma unroll
;   for (int r = 0; r < 16; ++r) ps += p1[r];
;   { auto rr = __builtin_amdgcn_permlane32_swap(__float_as_uint(ps), __float_as_uint(ps), false, false);
;     ps = __uint_as_float(rr[0]) + __uint_as_float(rr[1]); }
;   l_reg = l_reg * alpha + ps;
;     ...
;   PK4(p0, 0, pa0); PK4(p0, 8, pa1); PK4(p1, 0, pa2); PK4(p1, 8, pa3);
;     ...
; }
; template <int I> __device__ __forceinline__ void pv_step(f32x16* o, int vb, const bf16x8 (&pa)[4], s16x4 (&l)[3], s16x4 (&h)[3]) {
;   if constexpr (I + 2 < 32) pv_rd<(I + 2 < 32 ? I + 2 : 0)>(vb, l[(I + 2) % 3], h[(I + 2) % 3]);
;   if constexpr (I + 2 < 32) asm volatile("s_waitcnt lgkmcnt(4)" ::: "memory"); else if constexpr (I + 1 < 32) asm volatile("s_waitcnt lgkmcnt(2)" ::: "memory"); else asm volatile("s_waitcnt lgkmcnt(0)" ::: "memory");
;   SBAR();
;   const s16x4 L = l[I % 3], H = h[I % 3];
;   o[I >> 2] = __builtin_amdgcn_mfma_f32_32x32x16_bf16(pa[I & 3], (bf16x8){L[0], L[1], L[2], L[3], H[0], H[1], H[2], H[3]}, o[I >> 2], 0, 0, 0);
;   SBAR();
;   if constexpr (I + 1 < 32) pv_step<(I + 1 < 32 ? I + 1 : 31)>(o, vb, pa, l, h);
; }
; __device__ __forceinline__ void pv_all_rolling(f32x16* o, int vb, bf16x8 pa0, bf16x8 pa1, bf16x8 pa2, bf16x8 pa3) {
;   const bf16x8 pa[4] = {pa0, pa1, pa2, pa3}; s16x4 l[3], h[3];
;   asm volatile("s_waitcnt lgkmcnt(0)" ::: "memory");
;   pv_rd<0>(vb, l[0], h[0]); pv_rd<1>(vb, l[1], h[1]);
;   pv_step<0>(o, vb, pa, l, h);
.LBB0_429:
	v_cndmask_b32_e64 v246, v223, v246, s[6:7]
	v_mul_f32_e32 v194, 0xbe0293ee, v246
	v_fmamk_f32 v146, v146, 0x3e0293ee, v194
	v_fmamk_f32 v147, v147, 0x3e0293ee, v194
	v_fmamk_f32 v148, v148, 0x3e0293ee, v194
	v_fmamk_f32 v149, v149, 0x3e0293ee, v194
	v_fmamk_f32 v150, v150, 0x3e0293ee, v194
	v_fmamk_f32 v151, v151, 0x3e0293ee, v194
	v_fmamk_f32 v152, v152, 0x3e0293ee, v194
	v_fmamk_f32 v153, v153, 0x3e0293ee, v194
	v_fmamk_f32 v154, v154, 0x3e0293ee, v194
	v_fmamk_f32 v155, v155, 0x3e0293ee, v194
	v_fmamk_f32 v156, v156, 0x3e0293ee, v194
	v_fmamk_f32 v157, v157, 0x3e0293ee, v194
	v_fmamk_f32 v158, v158, 0x3e0293ee, v194
	v_fmamk_f32 v159, v159, 0x3e0293ee, v194
	v_fmamk_f32 v160, v160, 0x3e0293ee, v194
	v_fmamk_f32 v161, v161, 0x3e0293ee, v194
	v_fmamk_f32 v130, v130, 0x3e0293ee, v194
	v_fmamk_f32 v131, v131, 0x3e0293ee, v194
	v_fmamk_f32 v132, v132, 0x3e0293ee, v194
	v_fmamk_f32 v133, v133, 0x3e0293ee, v194
	v_fmamk_f32 v134, v134, 0x3e0293ee, v194
	v_fmamk_f32 v135, v135, 0x3e0293ee, v194
	v_fmamk_f32 v136, v136, 0x3e0293ee, v194
	v_fmamk_f32 v137, v137, 0x3e0293ee, v194
	v_fmamk_f32 v138, v138, 0x3e0293ee, v194
	v_fmamk_f32 v139, v139, 0x3e0293ee, v194
	v_fmamk_f32 v140, v140, 0x3e0293ee, v194
	v_fmamk_f32 v141, v141, 0x3e0293ee, v194
	v_fmamk_f32 v142, v142, 0x3e0293ee, v194
	v_fmamk_f32 v143, v143, 0x3e0293ee, v194
	v_fmamk_f32 v144, v144, 0x3e0293ee, v194
	v_fmac_f32_e32 v194, 0x3e0293ee, v145
	v_exp_f32_e32 v145, v146
	v_exp_f32_e32 v146, v147
	v_exp_f32_e32 v147, v148
	v_exp_f32_e32 v148, v149
	v_exp_f32_e32 v149, v150
	v_exp_f32_e32 v150, v151
	v_exp_f32_e32 v151, v152
	v_exp_f32_e32 v152, v153
	v_exp_f32_e32 v153, v154
	v_exp_f32_e32 v154, v155
	v_exp_f32_e32 v155, v156
	v_exp_f32_e32 v156, v157
	v_exp_f32_e32 v157, v158
	v_exp_f32_e32 v158, v159
	v_exp_f32_e32 v159, v160
	v_exp_f32_e32 v160, v161
	v_add_f32_e32 v161, v247, v248
	v_fmac_f32_e32 v161, v245, v0
	v_exp_f32_e32 v0, v130
	v_add_f32_e32 v130, 0, v145
	v_add_f32_e32 v130, v146, v130
	v_add_f32_e32 v130, v147, v130
	v_add_f32_e32 v130, v148, v130
	v_add_f32_e32 v130, v149, v130
	v_add_f32_e32 v130, v150, v130
	v_add_f32_e32 v130, v151, v130
	v_add_f32_e32 v130, v152, v130
	v_add_f32_e32 v130, v153, v130
	v_add_f32_e32 v130, v154, v130
	v_add_f32_e32 v130, v155, v130
	v_add_f32_e32 v130, v156, v130
	v_add_f32_e32 v130, v157, v130
	v_exp_f32_e32 v195, v131
	v_add_f32_e32 v130, v158, v130
	v_exp_f32_e32 v196, v132
	v_add_f32_e32 v130, v159, v130
	v_exp_f32_e32 v197, v133
	v_add_f32_e32 v130, v160, v130
	v_exp_f32_e32 v198, v134
	v_add_f32_e32 v130, v0, v130
	v_exp_f32_e32 v199, v135
	v_add_f32_e32 v130, v195, v130
	v_exp_f32_e32 v200, v136
	v_add_f32_e32 v130, v196, v130
	v_exp_f32_e32 v201, v137
	v_add_f32_e32 v130, v197, v130
	v_exp_f32_e32 v202, v138
	v_add_f32_e32 v130, v198, v130
	v_exp_f32_e32 v203, v139
	v_add_f32_e32 v130, v199, v130
	v_exp_f32_e32 v204, v140
	v_add_f32_e32 v130, v200, v130
	v_exp_f32_e32 v205, v141
	v_add_f32_e32 v130, v201, v130
	v_exp_f32_e32 v206, v142
	v_add_f32_e32 v130, v202, v130
	v_exp_f32_e32 v207, v143
	v_add_f32_e32 v130, v203, v130
	v_exp_f32_e32 v208, v144
	v_add_f32_e32 v130, v204, v130
	v_exp_f32_e32 v194, v194
	v_add_f32_e32 v130, v205, v130
	v_add_f32_e32 v130, v206, v130
	v_add_f32_e32 v130, v207, v130
	v_add_f32_e32 v130, v208, v130
	v_add_f32_e32 v130, v194, v130
	v_mov_b32_e32 v131, v130
	s_nop 1
	v_permlane32_swap_b32_e32 v130, v131
	v_add_f32_e32 v245, v130, v131
	v_fmac_f32_e32 v245, v161, v222
	s_waitcnt vmcnt(0)
	s_barrier
	s_setprio 0
	v_cvt_pk_bf16_f32 v130, v145, v146
	v_cvt_pk_bf16_f32 v131, v147, v148
	v_cvt_pk_bf16_f32 v132, v149, v150
	v_cvt_pk_bf16_f32 v133, v151, v152
	v_cvt_pk_bf16_f32 v134, v153, v154
	v_cvt_pk_bf16_f32 v135, v155, v156
	v_cvt_pk_bf16_f32 v136, v157, v158
	v_cvt_pk_bf16_f32 v137, v159, v160
	v_cvt_pk_bf16_f32 v138, v0, v195
	v_cvt_pk_bf16_f32 v139, v196, v197
	v_cvt_pk_bf16_f32 v140, v198, v199
	v_cvt_pk_bf16_f32 v141, v200, v201
	v_cvt_pk_bf16_f32 v142, v202, v203
	v_cvt_pk_bf16_f32 v143, v204, v205
	v_cvt_pk_bf16_f32 v144, v206, v207
	v_cvt_pk_bf16_f32 v145, v208, v194
	s_nop 0
	v_permlane32_swap_b32_e32 v130, v132
	v_permlane32_swap_b32_e32 v131, v133
	v_permlane32_swap_b32_e32 v134, v136
	v_permlane32_swap_b32_e32 v135, v137
	v_permlane32_swap_b32_e32 v138, v140
	v_permlane32_swap_b32_e32 v139, v141
	v_permlane32_swap_b32_e32 v142, v144
	v_permlane32_swap_b32_e32 v143, v145
	s_waitcnt lgkmcnt(0)
	ds_read_b64_tr_b16 v[146:147], v244 offset:0
	ds_read_b64_tr_b16 v[148:149], v244 offset:2048
	ds_read_b64_tr_b16 v[150:151], v244 offset:4096
	ds_read_b64_tr_b16 v[152:153], v244 offset:6144
	ds_read_b64_tr_b16 v[154:155], v244 offset:8192
	ds_read_b64_tr_b16 v[156:157], v244 offset:10240
	ds_read_b64_tr_b16 v[158:159], v244 offset:12288
	ds_read_b64_tr_b16 v[160:161], v244 offset:14336
	v_lshl_add_u64 v[232:233], v[218:219], 0, s[22:23]
	v_lshl_add_u64 v[232:233], v[232:233], 0, s[14:15]
	s_mov_b32 m0, s29
	s_nop 0
	global_load_lds_dwordx4 v[232:233], off
	s_waitcnt lgkmcnt(6)
	s_nop 0
	v_mfma_f32_32x32x16_bf16 v[114:129], v[130:133], v[146:149], v[114:129]
	ds_read_b64_tr_b16 v[146:147], v244 offset:512
	ds_read_b64_tr_b16 v[148:149], v244 offset:2560
	v_lshl_add_u64 v[232:233], v[218:219], 0, s[22:23]
	v_lshl_add_u64 v[232:233], v[232:233], 0, s[16:17]
	s_mov_b32 m0, s65
	s_nop 0
	global_load_lds_dwordx4 v[232:233], off
	s_waitcnt lgkmcnt(6)
	v_mfma_f32_32x32x16_bf16 v[114:129], v[134:137], v[150:153], v[114:129]
	ds_read_b64_tr_b16 v[150:151], v244 offset:4608
	ds_read_b64_tr_b16 v[152:153], v244 offset:6656
	v_lshl_add_u64 v[232:233], v[220:221], 0, s[22:23]
	v_lshl_add_u64 v[232:233], v[232:233], 0, s[14:15]
	s_mov_b32 m0, s68
	s_nop 0
	global_load_lds_dwordx4 v[232:233], off
	s_waitcnt lgkmcnt(6)
; #define SBAR() __builtin_amdgcn_sched_barrier(0)
; #define DPUB() do { asm volatile("s_waitcnt vmcnt(0)" ::: "memory"); __syncthreads(); } while (0)
; #define DTILE(b) do { f32x16 p0 = f32x16{}, p1 = f32x16{}; float mn, al; bf16x8 pa0, pa1, pa2, pa3; \
;     qkt_rolling<(b) * DA_KB>(p0, p1, ka0, qr); partialSM(p0, p1, m_reg, mn, al); DRESC(al); finishSM(p0, p1, al, l_reg, pa0, pa1, pa2, pa3); SBAR(); \
;     pv_all_rolling(o, vb0 + (b) * DA_VB, pa0, pa1, pa2, pa3); } while (0)
; template <int I> __device__ __forceinline__ void pv_rd(int vb, s16x4& l, s16x4& h) {
;   constexpr int D0 = I >> 2, KS = I & 3, IMG = (D0 >> 2) * 16384, DD = D0 & 3;
;   l = tr_read<IMG + v_rd_off(DD, KS, 0)>(vb); h = tr_read<IMG + v_rd_off(DD, KS, 1)>(vb);
; }
; template <int I> __device__ __forceinline__ void pv_step(f32x16* o, int vb, const bf16x8 (&pa)[4], s16x4 (&l)[3], s16x4 (&h)[3]) {
;   if constexpr (I + 2 < 32) pv_rd<(I + 2 < 32 ? I + 2 : 0)>(vb, l[(I + 2) % 3], h[(I + 2) % 3]);
;   if constexpr (I + 2 < 32) asm volatile("s_waitcnt lgkmcnt(4)" ::: "memory"); else if constexpr (I + 1 < 32) asm volatile("s_waitcnt lgkmcnt(2)" ::: "memory"); else asm volatile("s_waitcnt lgkmcnt(0)" ::: "memory");
;   SBAR();
;   const s16x4 L = l[I % 3], H = h[I % 3];
;   o[I >> 2] = __builtin_amdgcn_mfma_f32_32x32x16_bf16(pa[I & 3], (bf16x8){L[0], L[1], L[2], L[3], H[0], H[1], H[2], H[3]}, o[I >> 2], 0, 0, 0);
;   SBAR();
;   if constexpr (I + 1 < 32) pv_step<(I + 1 < 32 ? I + 1 : 31)>(o, vb, pa, l, h);
; }
; __device__ __forceinline__ void pv_all_rolling(f32x16* o, int vb, bf16x8 pa0, bf16x8 pa1, bf16x8 pa2, bf16x8 pa3) {
;   const bf16x8 pa[4] = {pa0, pa1, pa2, pa3}; s16x4 l[3], h[3];
;   asm volatile("s_waitcnt lgkmcnt(0)" ::: "memory");
;   pv_rd<0>(vb, l[0], h[0]); pv_rd<1>(vb, l[1], h[1]);
;   pv_step<0>(o, vb, pa, l, h);
; }
; __device__ __forceinline__ void unit_body_da(const Unit& U, char* lds) {
;     ...
;   for (int j = 0; j < NT; j += 2) {
;     DDMA(j + 1, 1); SBAR();
;     DTILE(0); SBAR(); DPUB();
;     if (j + 2 < NT) DDMA(j + 2, 0); SBAR();
;     DTILE(1); SBAR(); DPUB();
;   }
	v_mfma_f32_32x32x16_bf16 v[114:129], v[138:141], v[154:157], v[114:129]
	ds_read_b64_tr_b16 v[154:155], v244 offset:8704
	ds_read_b64_tr_b16 v[156:157], v244 offset:10752
	v_lshl_add_u64 v[232:233], v[220:221], 0, s[22:23]
	v_lshl_add_u64 v[232:233], v[232:233], 0, s[16:17]
	s_mov_b32 m0, s69
	s_nop 0
	global_load_lds_dwordx4 v[232:233], off
	s_waitcnt lgkmcnt(6)
	v_mfma_f32_32x32x16_bf16 v[114:129], v[142:145], v[158:161], v[114:129]
	ds_read_b64_tr_b16 v[158:159], v244 offset:12800
	ds_read_b64_tr_b16 v[160:161], v244 offset:14848
	s_waitcnt lgkmcnt(6)
	v_mfma_f32_32x32x16_bf16 v[98:113], v[130:133], v[146:149], v[98:113]
	ds_read_b64_tr_b16 v[146:147], v244 offset:1024
	ds_read_b64_tr_b16 v[148:149], v244 offset:3072
	s_waitcnt lgkmcnt(6)
	v_mfma_f32_32x32x16_bf16 v[98:113], v[134:137], v[150:153], v[98:113]
	ds_read_b64_tr_b16 v[150:151], v244 offset:5120
	ds_read_b64_tr_b16 v[152:153], v244 offset:7168
	s_waitcnt lgkmcnt(6)
	v_mfma_f32_32x32x16_bf16 v[98:113], v[138:141], v[154:157], v[98:113]
	ds_read_b64_tr_b16 v[154:155], v244 offset:9216
	ds_read_b64_tr_b16 v[156:157], v244 offset:11264
	s_waitcnt lgkmcnt(6)
	v_mfma_f32_32x32x16_bf16 v[98:113], v[142:145], v[158:161], v[98:113]
	ds_read_b64_tr_b16 v[158:159], v244 offset:13312
	ds_read_b64_tr_b16 v[160:161], v244 offset:15360
	s_cmp_lt_u32 s25, 0x2000
	s_cbranch_scc1 .Lda_l0_s1_nolk
	v_lshl_add_u64 v[232:233], v[224:225], 0, s[14:15]
	v_lshl_add_u64 v[232:233], v[232:233], 0, s[10:11]
	s_add_i32 m0, s62, s25
	s_nop 0
	global_load_lds_dwordx4 v[232:233], off
	v_lshl_add_u64 v[232:233], v[228:229], 0, s[14:15]
	v_lshl_add_u64 v[232:233], v[232:233], 0, s[10:11]
	s_add_i32 m0, s62, s66
	s_nop 0
	global_load_lds_dwordx4 v[232:233], off
.Lda_l0_s1_nolk:
	s_waitcnt lgkmcnt(6)
	v_mfma_f32_32x32x16_bf16 v[82:97], v[130:133], v[146:149], v[82:97]
	ds_read_b64_tr_b16 v[146:147], v244 offset:1536
	ds_read_b64_tr_b16 v[148:149], v244 offset:3584
	s_waitcnt lgkmcnt(6)
	v_mfma_f32_32x32x16_bf16 v[82:97], v[134:137], v[150:153], v[82:97]
	ds_read_b64_tr_b16 v[150:151], v244 offset:5632
	ds_read_b64_tr_b16 v[152:153], v244 offset:7680
	s_waitcnt lgkmcnt(6)
	v_mfma_f32_32x32x16_bf16 v[82:97], v[138:141], v[154:157], v[82:97]
	ds_read_b64_tr_b16 v[154:155], v244 offset:9728
	ds_read_b64_tr_b16 v[156:157], v244 offset:11776
	s_waitcnt lgkmcnt(6)
	v_mfma_f32_32x32x16_bf16 v[82:97], v[142:145], v[158:161], v[82:97]
	ds_read_b64_tr_b16 v[158:159], v244 offset:13824
	ds_read_b64_tr_b16 v[160:161], v244 offset:15872
	s_waitcnt lgkmcnt(6)
	v_mfma_f32_32x32x16_bf16 v[66:81], v[130:133], v[146:149], v[66:81]
	ds_read_b64_tr_b16 v[146:147], v244 offset:16384
	ds_read_b64_tr_b16 v[148:149], v244 offset:18432
	s_waitcnt lgkmcnt(6)
	v_mfma_f32_32x32x16_bf16 v[66:81], v[134:137], v[150:153], v[66:81]
	ds_read_b64_tr_b16 v[150:151], v244 offset:20480
	ds_read_b64_tr_b16 v[152:153], v244 offset:22528
	s_waitcnt lgkmcnt(6)
	v_mfma_f32_32x32x16_bf16 v[66:81], v[138:141], v[154:157], v[66:81]
	ds_read_b64_tr_b16 v[154:155], v244 offset:24576
	ds_read_b64_tr_b16 v[156:157], v244 offset:26624
	s_waitcnt lgkmcnt(6)
	v_mfma_f32_32x32x16_bf16 v[66:81], v[142:145], v[158:161], v[66:81]
	ds_read_b64_tr_b16 v[158:159], v244 offset:28672
	ds_read_b64_tr_b16 v[160:161], v244 offset:30720
	s_waitcnt lgkmcnt(6)
	v_mfma_f32_32x32x16_bf16 v[50:65], v[130:133], v[146:149], v[50:65]
	ds_read_b64_tr_b16 v[146:147], v244 offset:16896
	ds_read_b64_tr_b16 v[148:149], v244 offset:18944
	s_waitcnt lgkmcnt(6)
	v_mfma_f32_32x32x16_bf16 v[50:65], v[134:137], v[150:153], v[50:65]
	ds_read_b64_tr_b16 v[150:151], v244 offset:20992
	ds_read_b64_tr_b16 v[152:153], v244 offset:23040
	s_waitcnt lgkmcnt(6)
	v_mfma_f32_32x32x16_bf16 v[50:65], v[138:141], v[154:157], v[50:65]
	ds_read_b64_tr_b16 v[154:155], v244 offset:25088
	ds_read_b64_tr_b16 v[156:157], v244 offset:27136
	s_waitcnt lgkmcnt(6)
	v_mfma_f32_32x32x16_bf16 v[50:65], v[142:145], v[158:161], v[50:65]
	ds_read_b64_tr_b16 v[158:159], v244 offset:29184
	ds_read_b64_tr_b16 v[160:161], v244 offset:31232
	s_waitcnt lgkmcnt(6)
	v_mfma_f32_32x32x16_bf16 v[34:49], v[130:133], v[146:149], v[34:49]
	ds_read_b64_tr_b16 v[146:147], v244 offset:17408
	ds_read_b64_tr_b16 v[148:149], v244 offset:19456
	s_waitcnt lgkmcnt(6)
	v_mfma_f32_32x32x16_bf16 v[34:49], v[134:137], v[150:153], v[34:49]
	ds_read_b64_tr_b16 v[150:151], v244 offset:21504
	ds_read_b64_tr_b16 v[152:153], v244 offset:23552
	s_waitcnt lgkmcnt(6)
	v_mfma_f32_32x32x16_bf16 v[34:49], v[138:141], v[154:157], v[34:49]
	ds_read_b64_tr_b16 v[154:155], v244 offset:25600
	ds_read_b64_tr_b16 v[156:157], v244 offset:27648
	s_waitcnt lgkmcnt(6)
	v_mfma_f32_32x32x16_bf16 v[34:49], v[142:145], v[158:161], v[34:49]
	ds_read_b64_tr_b16 v[158:159], v244 offset:29696
	ds_read_b64_tr_b16 v[160:161], v244 offset:31744
	s_waitcnt lgkmcnt(6)
	v_mfma_f32_32x32x16_bf16 v[18:33], v[130:133], v[146:149], v[18:33]
	ds_read_b64_tr_b16 v[146:147], v244 offset:17920
	ds_read_b64_tr_b16 v[148:149], v244 offset:19968
	s_waitcnt lgkmcnt(6)
	v_mfma_f32_32x32x16_bf16 v[18:33], v[134:137], v[150:153], v[18:33]
	ds_read_b64_tr_b16 v[150:151], v244 offset:22016
	ds_read_b64_tr_b16 v[152:153], v244 offset:24064
	s_waitcnt lgkmcnt(6)
	v_mfma_f32_32x32x16_bf16 v[18:33], v[138:141], v[154:157], v[18:33]
	ds_read_b64_tr_b16 v[154:155], v244 offset:26112
	ds_read_b64_tr_b16 v[156:157], v244 offset:28160
	s_waitcnt lgkmcnt(6)
	v_mfma_f32_32x32x16_bf16 v[18:33], v[142:145], v[158:161], v[18:33]
	ds_read_b64_tr_b16 v[158:159], v244 offset:30208
	ds_read_b64_tr_b16 v[160:161], v244 offset:32256
	ds_read_b128 v[194:197], v235 offset:0
	ds_read_b128 v[198:201], v236 offset:0
	ds_read_b128 v[202:205], v238 offset:0
	ds_read_b128 v[206:209], v239 offset:0
	s_waitcnt lgkmcnt(10)
	v_mfma_f32_32x32x16_bf16 v[2:17], v[130:133], v[146:149], v[2:17]
	s_waitcnt lgkmcnt(8)
	v_mfma_f32_32x32x16_bf16 v[2:17], v[134:137], v[150:153], v[2:17]
	s_waitcnt lgkmcnt(6)
	v_mfma_f32_32x32x16_bf16 v[2:17], v[138:141], v[154:157], v[2:17]
	s_waitcnt lgkmcnt(4)
	v_mfma_f32_32x32x16_bf16 v[2:17], v[142:145], v[158:161], v[2:17]
	s_waitcnt vmcnt(0)
	s_add_u32 s22, s22, 0x180000
	s_addc_u32 s23, s23, 0
	s_add_i32 s80, s80, 2
	s_and_b64 vcc, exec, s[46:47]
	s_waitcnt vmcnt(0) lgkmcnt(0)
	s_barrier
	s_cbranch_vccnz .LBB0_439
; #define SBAR() __builtin_amdgcn_sched_barrier(0)
; __device__ __forceinline__ void partialSM(f32x16& p0, f32x16& p1, float& m_reg, float& mn, float& alpha) {
;   constexpr float C = SCALE * 1.4426950408889634f;
;   float pmax = p0[0];
; #pragma unroll
;   for (int r = 1; r < 16; ++r) pmax = fmaxf(pmax, p0[r]);
; #pragma unroll
;   for (int r = 0; r < 16; ++r) pmax = fmaxf(pmax, p1[r]);
;   { auto rr = __builtin_amdgcn_permlane32_swap(__float_as_uint(pmax), __float_as_uint(pmax), false, false);
;     pmax = fmaxf(__uint_as_float(rr[0]), __uint_as_float(rr[1])); }
;   if (__builtin_expect(__all(pmax - m_reg <= THR / SCALE), 1)) { mn = m_reg; alpha = 1.f; }
; template <int OFF> __device__ __forceinline__ bf16x8 k_read(int a) { bf16x8 r; asm volatile("ds_read_b128 %0, %1 offset:%2" : "=&v"(r) : "v"(a), "i"(OFF) : "memory"); return r; }
; template <int BUFOFF, int D0> __device__ __forceinline__ void qk_step(f32x16& p0, f32x16& p1, int ka0, const bf16x8 (&qr)[8], bf16x8 (&k0)[2], bf16x8 (&k1)[2]) {
;   if constexpr (D0 + 1 < 8) { const int a_ = ka0 ^ ((D0 + 1) << 5); k0[(D0 + 1) & 1] = k_read<BUFOFF>(a_); k1[(D0 + 1) & 1] = k_read<BUFOFF + 8192>(a_); }
;   if constexpr (D0 + 1 < 8) asm volatile("s_waitcnt lgkmcnt(2)" ::: "memory"); else asm volatile("s_waitcnt lgkmcnt(0)" ::: "memory");
;   SBAR();
;   p0 = __builtin_amdgcn_mfma_f32_32x32x16_bf16(k0[D0 & 1], qr[D0], p0, 0, 0, 0);
;   p1 = __builtin_amdgcn_mfma_f32_32x32x16_bf16(k1[D0 & 1], qr[D0], p1, 0, 0, 0);
;   SBAR();
;   if constexpr (D0 + 1 < 8) qk_step<BUFOFF, (D0 + 1 < 8 ? D0 + 1 : 7)>(p0, p1, ka0, qr, k0, k1);
; }
; template <int BUFOFF> __device__ __forceinline__ void qkt_rolling(f32x16& p0, f32x16& p1, int ka0, const bf16x8 (&qr)[8]) {
;   bf16x8 k0[2], k1[2];
;   asm volatile("s_waitcnt lgkmcnt(0)" ::: "memory");
;   k0[0] = k_read<BUFOFF>(ka0); k1[0] = k_read<BUFOFF + 8192>(ka0);
;   qk_step<BUFOFF, 0>(p0, p1, ka0, qr, k0, k1);
; }
.LBB0_430:
	s_setprio 1
	v_lshl_add_u64 v[224:225], v[214:215], 0, s[22:23]
	v_lshl_add_u64 v[228:229], v[216:217], 0, s[22:23]
	s_waitcnt lgkmcnt(0)
	ds_read_b128 v[130:133], v240 offset:0
	ds_read_b128 v[134:137], v241 offset:0
	ds_read_b128 v[138:141], v242 offset:0
	ds_read_b128 v[142:145], v243 offset:0
	s_cmp_lt_u32 s25, 0x2000
	s_cbranch_scc0 .Lda_l0_s0_nok
	v_lshl_add_u64 v[232:233], v[224:225], 0, s[10:11]
	s_add_i32 m0, s62, s25
	s_nop 0
	global_load_lds_dwordx4 v[232:233], off
	v_lshl_add_u64 v[232:233], v[228:229], 0, s[10:11]
	s_add_i32 m0, s62, s66
	s_nop 0
	global_load_lds_dwordx4 v[232:233], off
.Lda_l0_s0_nok:
	s_waitcnt lgkmcnt(7)
	s_nop 0
	v_mfma_f32_32x32x16_bf16 v[146:161], v[194:197], v[162:165], 0
	ds_read_b128 v[194:197], v235 offset:8192
	s_waitcnt lgkmcnt(7)
	v_mfma_f32_32x32x16_bf16 v[146:161], v[198:201], v[166:169], v[146:161]
	ds_read_b128 v[198:201], v236 offset:8192
	s_waitcnt lgkmcnt(7)
	v_mfma_f32_32x32x16_bf16 v[146:161], v[202:205], v[170:173], v[146:161]
	ds_read_b128 v[202:205], v238 offset:8192
	s_waitcnt lgkmcnt(7)
	v_mfma_f32_32x32x16_bf16 v[146:161], v[206:209], v[174:177], v[146:161]
	ds_read_b128 v[206:209], v239 offset:8192
	s_waitcnt lgkmcnt(7)
	v_mfma_f32_32x32x16_bf16 v[146:161], v[130:133], v[178:181], v[146:161]
	s_waitcnt lgkmcnt(6)
	v_mfma_f32_32x32x16_bf16 v[146:161], v[134:137], v[182:185], v[146:161]
	s_waitcnt lgkmcnt(5)
	v_mfma_f32_32x32x16_bf16 v[146:161], v[138:141], v[186:189], v[146:161]
	s_waitcnt lgkmcnt(4)
	v_mfma_f32_32x32x16_bf16 v[146:161], v[142:145], v[190:193], v[146:161]
	s_waitcnt lgkmcnt(3)
	v_mfma_f32_32x32x16_bf16 v[130:145], v[194:197], v[162:165], 0
	ds_read_b128 v[194:197], v240 offset:8192
	s_waitcnt lgkmcnt(3)
	v_mfma_f32_32x32x16_bf16 v[130:145], v[198:201], v[166:169], v[130:145]
	ds_read_b128 v[198:201], v241 offset:8192
	s_waitcnt lgkmcnt(3)
	v_mfma_f32_32x32x16_bf16 v[130:145], v[202:205], v[170:173], v[130:145]
	ds_read_b128 v[202:205], v242 offset:8192
	s_waitcnt lgkmcnt(3)
	v_mfma_f32_32x32x16_bf16 v[130:145], v[206:209], v[174:177], v[130:145]
	ds_read_b128 v[206:209], v243 offset:8192
	s_waitcnt lgkmcnt(3)
	v_mfma_f32_32x32x16_bf16 v[130:145], v[194:197], v[178:181], v[130:145]
	s_waitcnt lgkmcnt(2)
	v_mfma_f32_32x32x16_bf16 v[130:145], v[198:201], v[182:185], v[130:145]
	s_waitcnt lgkmcnt(1)
	v_mfma_f32_32x32x16_bf16 v[130:145], v[202:205], v[186:189], v[130:145]
	s_waitcnt lgkmcnt(0)
	v_mfma_f32_32x32x16_bf16 v[130:145], v[206:209], v[190:193], v[130:145]
	s_setprio 0
	v_max3_f32 v0, v146, v147, v148
	v_max3_f32 v194, v154, v155, v156
	v_max3_f32 v0, v0, v149, v150
	v_max3_f32 v194, v194, v157, v158
	v_max3_f32 v0, v0, v151, v152
	v_max3_f32 v194, v194, v159, v160
	v_max_f32_e32 v0, v0, v153
	v_max_f32_e32 v194, v194, v161
	s_nop 4
	v_max3_f32 v196, v130, v131, v132
	v_max3_f32 v197, v138, v139, v140
	v_max3_f32 v196, v196, v133, v134
	v_max3_f32 v197, v197, v141, v142
	v_max3_f32 v196, v196, v135, v136
	v_max3_f32 v197, v197, v143, v144
	v_max_f32_e32 v196, v196, v137
	v_max_f32_e32 v197, v197, v145
	v_max3_f32 v0, v0, v194, v196
	v_max_f32_e32 v0, v0, v197
	v_mov_b32_e32 v194, v0
	s_nop 1
	v_permlane32_swap_b32_e32 v0, v194
	v_max_f32_e32 v0, v0, v194
	v_sub_f32_e32 v194, v0, v246
	v_cmp_ge_f32_e32 vcc, s63, v194
	s_cmp_eq_u64 vcc, exec
	s_cbranch_scc0 .Lda_slow_l0_3
	s_mov_b64 s[6:7], -1
	v_mov_b32_e32 v0, 1.0
	s_branch .LBB0_434

; __device__ __forceinline__ void partialSM(f32x16& p0, f32x16& p1, float& m_reg, float& mn, float& alpha) {
;     ...
;   float mnC = -mn * C;
; #pragma unroll
;   for (int r = 0; r < 16; ++r) p0[r] = fmaf(p0[r], C, mnC);
; #pragma unroll
;   for (int r = 0; r < 16; ++r) p1[r] = fmaf(p1[r], C, mnC);
; #pragma unroll
;   for (int r = 0; r < 16; ++r) p0[r] = __builtin_amdgcn_exp2f(p0[r]);
; }
; __device__ __forceinline__ void finishSM(f32x16& p0, f32x16& p1, float alpha, float& l_reg, bf16x8& pa0, bf16x8& pa1, bf16x8& pa2, bf16x8& pa3) {
; #pragma unroll
;   for (int r = 0; r < 16; ++r) p1[r] = __builtin_amdgcn_exp2f(p1[r]);
;   float ps = 0;
; #pragma unroll
;   for (int r = 0; r < 16; ++r) ps += p0[r];
; #pragma unroll
;   for (int r = 0; r < 16; ++r) ps += p1[r];
;   { auto rr = __builtin_amdgcn_permlane32_swap(__float_as_uint(ps), __float_as_uint(ps), false, false);
;     ps = __uint_as_float(rr[0]) + __uint_as_float(rr[1]); }
;   l_reg = l_reg * alpha + ps;
;     ...
;   PK4(p0, 0, pa0); PK4(p0, 8, pa1); PK4(p1, 0, pa2); PK4(p1, 8, pa3);
;     ...
; }
; template <int I> __device__ __forceinline__ void pv_rd(int vb, s16x4& l, s16x4& h) {
;   constexpr int D0 = I >> 2, KS = I & 3, IMG = (D0 >> 2) * 16384, DD = D0 & 3;
;   l = tr_read<IMG + v_rd_off(DD, KS, 0)>(vb); h = tr_read<IMG + v_rd_off(DD, KS, 1)>(vb);
; }
; template <int I> __device__ __forceinline__ void pv_step(f32x16* o, int vb, const bf16x8 (&pa)[4], s16x4 (&l)[3], s16x4 (&h)[3]) {
;   if constexpr (I + 2 < 32) pv_rd<(I + 2 < 32 ? I + 2 : 0)>(vb, l[(I + 2) % 3], h[(I + 2) % 3]);
;   if constexpr (I + 2 < 32) asm volatile("s_waitcnt lgkmcnt(4)" ::: "memory"); else if constexpr (I + 1 < 32) asm volatile("s_waitcnt lgkmcnt(2)" ::: "memory"); else asm volatile("s_waitcnt lgkmcnt(0)" ::: "memory");
;   SBAR();
;   const s16x4 L = l[I % 3], H = h[I % 3];
;   o[I >> 2] = __builtin_amdgcn_mfma_f32_32x32x16_bf16(pa[I & 3], (bf16x8){L[0], L[1], L[2], L[3], H[0], H[1], H[2], H[3]}, o[I >> 2], 0, 0, 0);
;   SBAR();
;   if constexpr (I + 1 < 32) pv_step<(I + 1 < 32 ? I + 1 : 31)>(o, vb, pa, l, h);
; }
; __device__ __forceinline__ void pv_all_rolling(f32x16* o, int vb, bf16x8 pa0, bf16x8 pa1, bf16x8 pa2, bf16x8 pa3) {
;   const bf16x8 pa[4] = {pa0, pa1, pa2, pa3}; s16x4 l[3], h[3];
;   asm volatile("s_waitcnt lgkmcnt(0)" ::: "memory");
;   pv_rd<0>(vb, l[0], h[0]); pv_rd<1>(vb, l[1], h[1]);
;   pv_step<0>(o, vb, pa, l, h);
.LBB0_434:
	v_cndmask_b32_e64 v246, v247, v246, s[6:7]
	v_mul_f32_e32 v194, 0xbe0293ee, v246
	v_fmamk_f32 v146, v146, 0x3e0293ee, v194
	v_fmamk_f32 v147, v147, 0x3e0293ee, v194
	v_fmamk_f32 v148, v148, 0x3e0293ee, v194
	v_fmamk_f32 v149, v149, 0x3e0293ee, v194
	v_fmamk_f32 v150, v150, 0x3e0293ee, v194
	v_fmamk_f32 v151, v151, 0x3e0293ee, v194
	v_fmamk_f32 v152, v152, 0x3e0293ee, v194
	v_fmamk_f32 v153, v153, 0x3e0293ee, v194
	v_fmamk_f32 v154, v154, 0x3e0293ee, v194
	v_fmamk_f32 v155, v155, 0x3e0293ee, v194
	v_fmamk_f32 v156, v156, 0x3e0293ee, v194
	v_fmamk_f32 v157, v157, 0x3e0293ee, v194
	v_fmamk_f32 v158, v158, 0x3e0293ee, v194
	v_fmamk_f32 v159, v159, 0x3e0293ee, v194
	v_fmamk_f32 v160, v160, 0x3e0293ee, v194
	v_fmamk_f32 v161, v161, 0x3e0293ee, v194
	v_fmamk_f32 v130, v130, 0x3e0293ee, v194
	v_fmamk_f32 v131, v131, 0x3e0293ee, v194
	v_fmamk_f32 v132, v132, 0x3e0293ee, v194
	v_fmamk_f32 v133, v133, 0x3e0293ee, v194
	v_fmamk_f32 v134, v134, 0x3e0293ee, v194
	v_fmamk_f32 v135, v135, 0x3e0293ee, v194
	v_fmamk_f32 v136, v136, 0x3e0293ee, v194
	v_fmamk_f32 v137, v137, 0x3e0293ee, v194
	v_fmamk_f32 v138, v138, 0x3e0293ee, v194
	v_fmamk_f32 v139, v139, 0x3e0293ee, v194
	v_fmamk_f32 v140, v140, 0x3e0293ee, v194
	v_fmamk_f32 v141, v141, 0x3e0293ee, v194
	v_fmamk_f32 v142, v142, 0x3e0293ee, v194
	v_fmamk_f32 v143, v143, 0x3e0293ee, v194
	v_fmamk_f32 v144, v144, 0x3e0293ee, v194
	v_fmac_f32_e32 v194, 0x3e0293ee, v145
	v_exp_f32_e32 v145, v146
	v_exp_f32_e32 v146, v147
	v_exp_f32_e32 v147, v148
	v_exp_f32_e32 v148, v149
	v_exp_f32_e32 v149, v150
	v_exp_f32_e32 v150, v151
	v_exp_f32_e32 v151, v152
	v_exp_f32_e32 v152, v153
	v_exp_f32_e32 v153, v154
	v_exp_f32_e32 v154, v155
	v_exp_f32_e32 v155, v156
	v_exp_f32_e32 v156, v157
	v_exp_f32_e32 v157, v158
	v_exp_f32_e32 v158, v159
	v_exp_f32_e32 v159, v160
	v_exp_f32_e32 v160, v161
	v_exp_f32_e32 v161, v130
	v_add_f32_e32 v130, 0, v145
	v_add_f32_e32 v130, v146, v130
	v_add_f32_e32 v130, v147, v130
	v_add_f32_e32 v130, v148, v130
	v_add_f32_e32 v130, v149, v130
	v_add_f32_e32 v130, v150, v130
	v_add_f32_e32 v130, v151, v130
	v_add_f32_e32 v130, v152, v130
	v_add_f32_e32 v130, v153, v130
	v_add_f32_e32 v130, v154, v130
	v_add_f32_e32 v130, v155, v130
	v_add_f32_e32 v130, v156, v130
	v_add_f32_e32 v130, v157, v130
	v_exp_f32_e32 v195, v131
	v_add_f32_e32 v130, v158, v130
	v_exp_f32_e32 v196, v132
	v_add_f32_e32 v130, v159, v130
	v_exp_f32_e32 v197, v133
	v_add_f32_e32 v130, v160, v130
	v_exp_f32_e32 v198, v134
	v_add_f32_e32 v130, v161, v130
	v_exp_f32_e32 v199, v135
	v_add_f32_e32 v130, v195, v130
	v_exp_f32_e32 v200, v136
	v_add_f32_e32 v130, v196, v130
	v_exp_f32_e32 v201, v137
	v_add_f32_e32 v130, v197, v130
	v_exp_f32_e32 v202, v138
	v_add_f32_e32 v130, v198, v130
	v_exp_f32_e32 v203, v139
	v_add_f32_e32 v130, v199, v130
	v_exp_f32_e32 v204, v140
	v_add_f32_e32 v130, v200, v130
	v_exp_f32_e32 v205, v141
	v_add_f32_e32 v130, v201, v130
	v_exp_f32_e32 v206, v142
	v_add_f32_e32 v130, v202, v130
	v_exp_f32_e32 v207, v143
	v_add_f32_e32 v130, v203, v130
	v_exp_f32_e32 v208, v144
	v_add_f32_e32 v130, v204, v130
	v_exp_f32_e32 v194, v194
	v_add_f32_e32 v130, v205, v130
	v_add_f32_e32 v130, v206, v130
	v_add_f32_e32 v130, v207, v130
	v_add_f32_e32 v130, v208, v130
	v_add_f32_e32 v247, v194, v130
	v_mov_b32_e32 v248, v247
	s_nop 1
	v_permlane32_swap_b32_e32 v247, v248
	s_waitcnt vmcnt(0)
	s_barrier
	s_setprio 0
	v_cvt_pk_bf16_f32 v130, v145, v146
	v_cvt_pk_bf16_f32 v131, v147, v148
	v_cvt_pk_bf16_f32 v132, v149, v150
	v_cvt_pk_bf16_f32 v133, v151, v152
	v_cvt_pk_bf16_f32 v134, v153, v154
	v_cvt_pk_bf16_f32 v135, v155, v156
	v_cvt_pk_bf16_f32 v136, v157, v158
	v_cvt_pk_bf16_f32 v137, v159, v160
	v_cvt_pk_bf16_f32 v138, v161, v195
	v_cvt_pk_bf16_f32 v139, v196, v197
	v_cvt_pk_bf16_f32 v140, v198, v199
	v_cvt_pk_bf16_f32 v141, v200, v201
	v_cvt_pk_bf16_f32 v142, v202, v203
	v_cvt_pk_bf16_f32 v143, v204, v205
	v_cvt_pk_bf16_f32 v144, v206, v207
	v_cvt_pk_bf16_f32 v145, v208, v194
	s_nop 0
	v_permlane32_swap_b32_e32 v130, v132
	v_permlane32_swap_b32_e32 v131, v133
	v_permlane32_swap_b32_e32 v134, v136
	v_permlane32_swap_b32_e32 v135, v137
	v_permlane32_swap_b32_e32 v138, v140
	v_permlane32_swap_b32_e32 v139, v141
	v_permlane32_swap_b32_e32 v142, v144
	v_permlane32_swap_b32_e32 v143, v145
	s_waitcnt lgkmcnt(0)
	ds_read_b64_tr_b16 v[146:147], v213 offset:0
	ds_read_b64_tr_b16 v[148:149], v213 offset:2048
	ds_read_b64_tr_b16 v[150:151], v213 offset:4096
	ds_read_b64_tr_b16 v[152:153], v213 offset:6144
	ds_read_b64_tr_b16 v[154:155], v213 offset:8192
	ds_read_b64_tr_b16 v[156:157], v213 offset:10240
	ds_read_b64_tr_b16 v[158:159], v213 offset:12288
	ds_read_b64_tr_b16 v[160:161], v213 offset:14336
	v_lshl_add_u64 v[232:233], v[218:219], 0, s[22:23]
	v_lshl_add_u64 v[232:233], v[232:233], 0, s[10:11]
	s_add_i32 m0, s29, 0x8000
	s_nop 0
	global_load_lds_dwordx4 v[232:233], off
	s_waitcnt lgkmcnt(6)
	s_nop 0
	v_mfma_f32_32x32x16_bf16 v[114:129], v[130:133], v[146:149], v[114:129]
	ds_read_b64_tr_b16 v[146:147], v213 offset:512
	ds_read_b64_tr_b16 v[148:149], v213 offset:2560
	v_lshl_add_u64 v[232:233], v[218:219], 0, s[22:23]
	v_lshl_add_u64 v[232:233], v[232:233], 0, s[12:13]
	s_add_i32 m0, s29, 0xc000
	s_nop 0
	global_load_lds_dwordx4 v[232:233], off
	s_waitcnt lgkmcnt(6)
	v_mfma_f32_32x32x16_bf16 v[114:129], v[134:137], v[150:153], v[114:129]
	ds_read_b64_tr_b16 v[150:151], v213 offset:4608
	ds_read_b64_tr_b16 v[152:153], v213 offset:6656
	v_lshl_add_u64 v[232:233], v[220:221], 0, s[22:23]
	v_lshl_add_u64 v[232:233], v[232:233], 0, s[10:11]
	s_add_i32 m0, s29, 0x8400
	s_nop 0
	global_load_lds_dwordx4 v[232:233], off
	s_waitcnt lgkmcnt(6)
	v_mfma_f32_32x32x16_bf16 v[114:129], v[138:141], v[154:157], v[114:129]
	ds_read_b64_tr_b16 v[154:155], v213 offset:8704
	ds_read_b64_tr_b16 v[156:157], v213 offset:10752
	v_lshl_add_u64 v[232:233], v[220:221], 0, s[22:23]
	v_lshl_add_u64 v[232:233], v[232:233], 0, s[12:13]
	s_add_i32 m0, s29, 0xc400
	s_nop 0
	global_load_lds_dwordx4 v[232:233], off
	s_waitcnt lgkmcnt(6)
	v_mfma_f32_32x32x16_bf16 v[114:129], v[142:145], v[158:161], v[114:129]
	ds_read_b64_tr_b16 v[158:159], v213 offset:12800
	ds_read_b64_tr_b16 v[160:161], v213 offset:14848
	s_waitcnt lgkmcnt(6)
	v_mfma_f32_32x32x16_bf16 v[98:113], v[130:133], v[146:149], v[98:113]
	ds_read_b64_tr_b16 v[146:147], v213 offset:1024
	ds_read_b64_tr_b16 v[148:149], v213 offset:3072
	s_waitcnt lgkmcnt(6)
	v_mfma_f32_32x32x16_bf16 v[98:113], v[134:137], v[150:153], v[98:113]
	ds_read_b64_tr_b16 v[150:151], v213 offset:5120
	ds_read_b64_tr_b16 v[152:153], v213 offset:7168
	s_waitcnt lgkmcnt(6)
	v_mfma_f32_32x32x16_bf16 v[98:113], v[138:141], v[154:157], v[98:113]
	ds_read_b64_tr_b16 v[154:155], v213 offset:9216
	ds_read_b64_tr_b16 v[156:157], v213 offset:11264
	s_waitcnt lgkmcnt(6)
	v_mfma_f32_32x32x16_bf16 v[98:113], v[142:145], v[158:161], v[98:113]
	ds_read_b64_tr_b16 v[158:159], v213 offset:13312
	ds_read_b64_tr_b16 v[160:161], v213 offset:15360
	s_cmp_lt_u32 s25, 0x2000
	s_cbranch_scc1 .Lda_l0_s0_nolk
; #define SBAR() __builtin_amdgcn_sched_barrier(0)
; #define DPUB() do { asm volatile("s_waitcnt vmcnt(0)" ::: "memory"); __syncthreads(); } while (0)
; #define DTILE(b) do { f32x16 p0 = f32x16{}, p1 = f32x16{}; float mn, al; bf16x8 pa0, pa1, pa2, pa3; \
;     qkt_rolling<(b) * DA_KB>(p0, p1, ka0, qr); partialSM(p0, p1, m_reg, mn, al); DRESC(al); finishSM(p0, p1, al, l_reg, pa0, pa1, pa2, pa3); SBAR(); \
;     pv_all_rolling(o, vb0 + (b) * DA_VB, pa0, pa1, pa2, pa3); } while (0)
; template <int I> __device__ __forceinline__ void pv_rd(int vb, s16x4& l, s16x4& h) {
;   constexpr int D0 = I >> 2, KS = I & 3, IMG = (D0 >> 2) * 16384, DD = D0 & 3;
;   l = tr_read<IMG + v_rd_off(DD, KS, 0)>(vb); h = tr_read<IMG + v_rd_off(DD, KS, 1)>(vb);
; }
; template <int I> __device__ __forceinline__ void pv_step(f32x16* o, int vb, const bf16x8 (&pa)[4], s16x4 (&l)[3], s16x4 (&h)[3]) {
;   if constexpr (I + 2 < 32) pv_rd<(I + 2 < 32 ? I + 2 : 0)>(vb, l[(I + 2) % 3], h[(I + 2) % 3]);
;   if constexpr (I + 2 < 32) asm volatile("s_waitcnt lgkmcnt(4)" ::: "memory"); else if constexpr (I + 1 < 32) asm volatile("s_waitcnt lgkmcnt(2)" ::: "memory"); else asm volatile("s_waitcnt lgkmcnt(0)" ::: "memory");
;   SBAR();
;   const s16x4 L = l[I % 3], H = h[I % 3];
;   o[I >> 2] = __builtin_amdgcn_mfma_f32_32x32x16_bf16(pa[I & 3], (bf16x8){L[0], L[1], L[2], L[3], H[0], H[1], H[2], H[3]}, o[I >> 2], 0, 0, 0);
;   SBAR();
;   if constexpr (I + 1 < 32) pv_step<(I + 1 < 32 ? I + 1 : 31)>(o, vb, pa, l, h);
; }
; __device__ __forceinline__ void pv_all_rolling(f32x16* o, int vb, bf16x8 pa0, bf16x8 pa1, bf16x8 pa2, bf16x8 pa3) {
;   const bf16x8 pa[4] = {pa0, pa1, pa2, pa3}; s16x4 l[3], h[3];
;   asm volatile("s_waitcnt lgkmcnt(0)" ::: "memory");
;   pv_rd<0>(vb, l[0], h[0]); pv_rd<1>(vb, l[1], h[1]);
;   pv_step<0>(o, vb, pa, l, h);
; }
; __device__ __forceinline__ void unit_body_da(const Unit& U, char* lds) {
;     ...
;   for (int j = 0; j < NT; j += 2) {
;     DDMA(j + 1, 1); SBAR();
;     DTILE(0); SBAR(); DPUB();
;     if (j + 2 < NT) DDMA(j + 2, 0); SBAR();
;     DTILE(1); SBAR(); DPUB();
;   }
	v_lshl_add_u64 v[232:233], v[224:225], 0, s[14:15]
	s_mov_b32 m0, s28
	s_nop 0
	global_load_lds_dwordx4 v[232:233], off
	v_lshl_add_u64 v[232:233], v[228:229], 0, s[14:15]
	s_mov_b32 m0, s67
	s_nop 0
	global_load_lds_dwordx4 v[232:233], off
.Lda_l0_s0_nolk:
	s_waitcnt lgkmcnt(6)
	v_mfma_f32_32x32x16_bf16 v[82:97], v[130:133], v[146:149], v[82:97]
	ds_read_b64_tr_b16 v[146:147], v213 offset:1536
	ds_read_b64_tr_b16 v[148:149], v213 offset:3584
	s_waitcnt lgkmcnt(6)
	v_mfma_f32_32x32x16_bf16 v[82:97], v[134:137], v[150:153], v[82:97]
	ds_read_b64_tr_b16 v[150:151], v213 offset:5632
	ds_read_b64_tr_b16 v[152:153], v213 offset:7680
	s_waitcnt lgkmcnt(6)
	v_mfma_f32_32x32x16_bf16 v[82:97], v[138:141], v[154:157], v[82:97]
	ds_read_b64_tr_b16 v[154:155], v213 offset:9728
	ds_read_b64_tr_b16 v[156:157], v213 offset:11776
	s_waitcnt lgkmcnt(6)
	v_mfma_f32_32x32x16_bf16 v[82:97], v[142:145], v[158:161], v[82:97]
	ds_read_b64_tr_b16 v[158:159], v213 offset:13824
	ds_read_b64_tr_b16 v[160:161], v213 offset:15872
	s_waitcnt lgkmcnt(6)
	v_mfma_f32_32x32x16_bf16 v[66:81], v[130:133], v[146:149], v[66:81]
	ds_read_b64_tr_b16 v[146:147], v213 offset:16384
	ds_read_b64_tr_b16 v[148:149], v213 offset:18432
	s_waitcnt lgkmcnt(6)
	v_mfma_f32_32x32x16_bf16 v[66:81], v[134:137], v[150:153], v[66:81]
	ds_read_b64_tr_b16 v[150:151], v213 offset:20480
	ds_read_b64_tr_b16 v[152:153], v213 offset:22528
	s_waitcnt lgkmcnt(6)
	v_mfma_f32_32x32x16_bf16 v[66:81], v[138:141], v[154:157], v[66:81]
	ds_read_b64_tr_b16 v[154:155], v213 offset:24576
	ds_read_b64_tr_b16 v[156:157], v213 offset:26624
	s_waitcnt lgkmcnt(6)
	v_mfma_f32_32x32x16_bf16 v[66:81], v[142:145], v[158:161], v[66:81]
	ds_read_b64_tr_b16 v[158:159], v213 offset:28672
	ds_read_b64_tr_b16 v[160:161], v213 offset:30720
	s_waitcnt lgkmcnt(6)
	v_mfma_f32_32x32x16_bf16 v[50:65], v[130:133], v[146:149], v[50:65]
	ds_read_b64_tr_b16 v[146:147], v213 offset:16896
	ds_read_b64_tr_b16 v[148:149], v213 offset:18944
	s_waitcnt lgkmcnt(6)
	v_mfma_f32_32x32x16_bf16 v[50:65], v[134:137], v[150:153], v[50:65]
	ds_read_b64_tr_b16 v[150:151], v213 offset:20992
	ds_read_b64_tr_b16 v[152:153], v213 offset:23040
	s_waitcnt lgkmcnt(6)
	v_mfma_f32_32x32x16_bf16 v[50:65], v[138:141], v[154:157], v[50:65]
	ds_read_b64_tr_b16 v[154:155], v213 offset:25088
	ds_read_b64_tr_b16 v[156:157], v213 offset:27136
	s_waitcnt lgkmcnt(6)
	v_mfma_f32_32x32x16_bf16 v[50:65], v[142:145], v[158:161], v[50:65]
	ds_read_b64_tr_b16 v[158:159], v213 offset:29184
	ds_read_b64_tr_b16 v[160:161], v213 offset:31232
	s_waitcnt lgkmcnt(6)
	v_mfma_f32_32x32x16_bf16 v[34:49], v[130:133], v[146:149], v[34:49]
	ds_read_b64_tr_b16 v[146:147], v213 offset:17408
	ds_read_b64_tr_b16 v[148:149], v213 offset:19456
	s_waitcnt lgkmcnt(6)
	v_mfma_f32_32x32x16_bf16 v[34:49], v[134:137], v[150:153], v[34:49]
	ds_read_b64_tr_b16 v[150:151], v213 offset:21504
	ds_read_b64_tr_b16 v[152:153], v213 offset:23552
	s_waitcnt lgkmcnt(6)
	v_mfma_f32_32x32x16_bf16 v[34:49], v[138:141], v[154:157], v[34:49]
	ds_read_b64_tr_b16 v[154:155], v213 offset:25600
	ds_read_b64_tr_b16 v[156:157], v213 offset:27648
	s_waitcnt lgkmcnt(6)
	v_mfma_f32_32x32x16_bf16 v[34:49], v[142:145], v[158:161], v[34:49]
	ds_read_b64_tr_b16 v[158:159], v213 offset:29696
	ds_read_b64_tr_b16 v[160:161], v213 offset:31744
	s_waitcnt lgkmcnt(6)
	v_mfma_f32_32x32x16_bf16 v[18:33], v[130:133], v[146:149], v[18:33]
	ds_read_b64_tr_b16 v[146:147], v213 offset:17920
	ds_read_b64_tr_b16 v[148:149], v213 offset:19968
	s_waitcnt lgkmcnt(6)
	v_mfma_f32_32x32x16_bf16 v[18:33], v[134:137], v[150:153], v[18:33]
	ds_read_b64_tr_b16 v[150:151], v213 offset:22016
	ds_read_b64_tr_b16 v[152:153], v213 offset:24064
	s_waitcnt lgkmcnt(6)
	v_mfma_f32_32x32x16_bf16 v[18:33], v[138:141], v[154:157], v[18:33]
	ds_read_b64_tr_b16 v[154:155], v213 offset:26112
	ds_read_b64_tr_b16 v[156:157], v213 offset:28160
	s_waitcnt lgkmcnt(6)
	v_mfma_f32_32x32x16_bf16 v[18:33], v[142:145], v[158:161], v[18:33]
	ds_read_b64_tr_b16 v[158:159], v213 offset:30208
	ds_read_b64_tr_b16 v[160:161], v213 offset:32256
	ds_read_b128 v[194:197], v235 offset:16384
	ds_read_b128 v[198:201], v236 offset:16384
	ds_read_b128 v[202:205], v238 offset:16384
	ds_read_b128 v[206:209], v239 offset:16384
	s_waitcnt lgkmcnt(10)
	v_mfma_f32_32x32x16_bf16 v[2:17], v[130:133], v[146:149], v[2:17]
	s_waitcnt lgkmcnt(8)
	v_mfma_f32_32x32x16_bf16 v[2:17], v[134:137], v[150:153], v[2:17]
	s_waitcnt lgkmcnt(6)
	v_mfma_f32_32x32x16_bf16 v[2:17], v[138:141], v[154:157], v[2:17]
	s_waitcnt lgkmcnt(4)
	v_mfma_f32_32x32x16_bf16 v[2:17], v[142:145], v[158:161], v[2:17]
	s_waitcnt vmcnt(0)
	s_cmp_ge_u32 s80, s0
	s_cselect_b64 s[46:47], -1, 0
	s_and_b64 vcc, exec, s[46:47]
	s_waitcnt vmcnt(0) lgkmcnt(0)
	s_barrier
; #define SBAR() __builtin_amdgcn_sched_barrier(0)
; __device__ __forceinline__ void partialSM(f32x16& p0, f32x16& p1, float& m_reg, float& mn, float& alpha) {
;   constexpr float C = SCALE * 1.4426950408889634f;
;   float pmax = p0[0];
; #pragma unroll
;   for (int r = 1; r < 16; ++r) pmax = fmaxf(pmax, p0[r]);
; #pragma unroll
;   for (int r = 0; r < 16; ++r) pmax = fmaxf(pmax, p1[r]);
;   { auto rr = __builtin_amdgcn_permlane32_swap(__float_as_uint(pmax), __float_as_uint(pmax), false, false);
;     pmax = fmaxf(__uint_as_float(rr[0]), __uint_as_float(rr[1])); }
;   if (__builtin_expect(__all(pmax - m_reg <= THR / SCALE), 1)) { mn = m_reg; alpha = 1.f; }
; template <int OFF> __device__ __forceinline__ bf16x8 k_read(int a) { bf16x8 r; asm volatile("ds_read_b128 %0, %1 offset:%2" : "=&v"(r) : "v"(a), "i"(OFF) : "memory"); return r; }
; template <int BUFOFF, int D0> __device__ __forceinline__ void qk_step(f32x16& p0, f32x16& p1, int ka0, const bf16x8 (&qr)[8], bf16x8 (&k0)[2], bf16x8 (&k1)[2]) {
;   if constexpr (D0 + 1 < 8) { const int a_ = ka0 ^ ((D0 + 1) << 5); k0[(D0 + 1) & 1] = k_read<BUFOFF>(a_); k1[(D0 + 1) & 1] = k_read<BUFOFF + 8192>(a_); }
;   if constexpr (D0 + 1 < 8) asm volatile("s_waitcnt lgkmcnt(2)" ::: "memory"); else asm volatile("s_waitcnt lgkmcnt(0)" ::: "memory");
;   SBAR();
;   p0 = __builtin_amdgcn_mfma_f32_32x32x16_bf16(k0[D0 & 1], qr[D0], p0, 0, 0, 0);
;   p1 = __builtin_amdgcn_mfma_f32_32x32x16_bf16(k1[D0 & 1], qr[D0], p1, 0, 0, 0);
;   SBAR();
;   if constexpr (D0 + 1 < 8) qk_step<BUFOFF, (D0 + 1 < 8 ? D0 + 1 : 7)>(p0, p1, ka0, qr, k0, k1);
; }
; template <int BUFOFF> __device__ __forceinline__ void qkt_rolling(f32x16& p0, f32x16& p1, int ka0, const bf16x8 (&qr)[8]) {
;   bf16x8 k0[2], k1[2];
;   asm volatile("s_waitcnt lgkmcnt(0)" ::: "memory");
;   k0[0] = k_read<BUFOFF>(ka0); k1[0] = k_read<BUFOFF + 8192>(ka0);
;   qk_step<BUFOFF, 0>(p0, p1, ka0, qr, k0, k1);
; }
.LBB0_436:
	s_setprio 1
	s_waitcnt lgkmcnt(0)
	ds_read_b128 v[130:133], v240 offset:16384
	ds_read_b128 v[134:137], v241 offset:16384
	ds_read_b128 v[138:141], v242 offset:16384
	ds_read_b128 v[142:145], v243 offset:16384
	s_cmp_lt_u32 s25, 0x2000
	s_cbranch_scc0 .Lda_l0_s1_nok
	v_lshl_add_u64 v[232:233], v[224:225], 0, s[14:15]
	s_mov_b32 m0, s28
	s_nop 0
	global_load_lds_dwordx4 v[232:233], off
	v_lshl_add_u64 v[232:233], v[228:229], 0, s[14:15]
	s_mov_b32 m0, s67
	s_nop 0
	global_load_lds_dwordx4 v[232:233], off
.Lda_l0_s1_nok:
	s_waitcnt lgkmcnt(7)
	s_nop 0
	v_mfma_f32_32x32x16_bf16 v[146:161], v[194:197], v[162:165], 0
	ds_read_b128 v[194:197], v235 offset:24576
	s_waitcnt lgkmcnt(7)
	v_mfma_f32_32x32x16_bf16 v[146:161], v[198:201], v[166:169], v[146:161]
	ds_read_b128 v[198:201], v236 offset:24576
	s_waitcnt lgkmcnt(7)
	v_mfma_f32_32x32x16_bf16 v[146:161], v[202:205], v[170:173], v[146:161]
	ds_read_b128 v[202:205], v238 offset:24576
	s_waitcnt lgkmcnt(7)
	v_mfma_f32_32x32x16_bf16 v[146:161], v[206:209], v[174:177], v[146:161]
	ds_read_b128 v[206:209], v239 offset:24576
	s_waitcnt lgkmcnt(7)
	v_mfma_f32_32x32x16_bf16 v[146:161], v[130:133], v[178:181], v[146:161]
	s_waitcnt lgkmcnt(6)
	v_mfma_f32_32x32x16_bf16 v[146:161], v[134:137], v[182:185], v[146:161]
	s_waitcnt lgkmcnt(5)
	v_mfma_f32_32x32x16_bf16 v[146:161], v[138:141], v[186:189], v[146:161]
	s_waitcnt lgkmcnt(4)
	v_mfma_f32_32x32x16_bf16 v[146:161], v[142:145], v[190:193], v[146:161]
	s_waitcnt lgkmcnt(3)
	v_mfma_f32_32x32x16_bf16 v[130:145], v[194:197], v[162:165], 0
	ds_read_b128 v[194:197], v240 offset:24576
	s_waitcnt lgkmcnt(3)
	v_mfma_f32_32x32x16_bf16 v[130:145], v[198:201], v[166:169], v[130:145]
	ds_read_b128 v[198:201], v241 offset:24576
	s_waitcnt lgkmcnt(3)
	v_mfma_f32_32x32x16_bf16 v[130:145], v[202:205], v[170:173], v[130:145]
	ds_read_b128 v[202:205], v242 offset:24576
	s_waitcnt lgkmcnt(3)
	v_mfma_f32_32x32x16_bf16 v[130:145], v[206:209], v[174:177], v[130:145]
	ds_read_b128 v[206:209], v243 offset:24576
	s_waitcnt lgkmcnt(3)
	v_mfma_f32_32x32x16_bf16 v[130:145], v[194:197], v[178:181], v[130:145]
	s_waitcnt lgkmcnt(2)
	v_mfma_f32_32x32x16_bf16 v[130:145], v[198:201], v[182:185], v[130:145]
	s_waitcnt lgkmcnt(1)
	v_mfma_f32_32x32x16_bf16 v[130:145], v[202:205], v[186:189], v[130:145]
	s_waitcnt lgkmcnt(0)
	v_mfma_f32_32x32x16_bf16 v[130:145], v[206:209], v[190:193], v[130:145]
	s_setprio 0
	v_max3_f32 v194, v146, v147, v148
	v_max3_f32 v195, v154, v155, v156
	v_max3_f32 v194, v194, v149, v150
	v_max3_f32 v195, v195, v157, v158
	v_max3_f32 v194, v194, v151, v152
	v_max3_f32 v195, v195, v159, v160
	v_max_f32_e32 v194, v194, v153
	v_max_f32_e32 v195, v195, v161
	s_nop 4
	v_max3_f32 v196, v130, v131, v132
	v_max3_f32 v197, v138, v139, v140
	v_max3_f32 v196, v196, v133, v134
	v_max3_f32 v197, v197, v141, v142
	v_max3_f32 v196, v196, v135, v136
	v_max3_f32 v197, v197, v143, v144
	v_max_f32_e32 v196, v196, v137
	v_max_f32_e32 v197, v197, v145
	v_max3_f32 v194, v194, v195, v196
	v_max_f32_e32 v194, v194, v197
	v_mov_b32_e32 v195, v194
	s_nop 1
	v_permlane32_swap_b32_e32 v194, v195
	v_max_f32_e32 v194, v194, v195
	v_sub_f32_e32 v195, v194, v246
	v_cmp_ge_f32_e32 vcc, s63, v195
	s_cmp_eq_u64 vcc, exec
	s_cbranch_scc0 .Lda_slow_l0_4
	s_mov_b64 s[6:7], -1
	v_mov_b32_e32 v222, 1.0
	s_branch .LBB0_429

; #define SBAR() __builtin_amdgcn_sched_barrier(0)
; __device__ __forceinline__ int v_rd_base(int lane) { return ((lane & 3) << 3) | (((lane >> 2) & 3) << 6) | (((lane >> 4) & 1) << 5) | (((lane >> 5) & 1) << 8); }
; #define DPUB() do { asm volatile("s_waitcnt vmcnt(0)" ::: "memory"); __syncthreads(); } while (0)
; __device__ __forceinline__ void unit_body_da(const Unit& U, char* lds) {
;   int tid = threadIdx.x; asm volatile("" : "+v"(tid)); const int wid = __builtin_amdgcn_readfirstlane(tid >> 6), lane = tid & 63, r32 = lane & 31, hi = lane >> 5;
;   char* V_lds = lds; char* K_lds = lds + 2 * DA_VB;
;   float* ws = (float*)(lds + DA_WS_OFF) + wid * 64; float* li_l = ws; float* al_l = ws + 32;
;   float m_reg = -1e30f, l_reg = 0; f32x16 o[8] = {}; bf16x8 qr[8];
;   const bf16_t* Qw = U.Q + (long)(wid * QBLK + r32) * LDP + hi * 8;
; #pragma unroll
;   for (int d0 = 0; d0 < 8; ++d0) qr[d0] = ld8(Qw + d0 * 16);
;   const int vb0 = (int)(uintptr_t)V_lds + v_rd_base(lane);
;   const int ka0 = (int)(uintptr_t)K_lds + KSWZ(r32, hi * 16);
;   constexpr float C = SCALE * 1.4426950408889634f;
;   unsigned koff[2], voff[2][2];
; #pragma unroll
;   for (int i = 0; i < 2; ++i) { const int ob = (2 * wid + i) * 1024 + lane * 16;
;     { const int row = ob >> 8, cpos = (ob >> 4) & 15, c = cpos ^ (row & 7); koff[i] = (unsigned)(row * LDP + c * 8); }
;     { const int st = ob >> 9, kk = (st >> 2) * 8 + ((ob >> 6) & 7), c = (st & 3) * 32 + ((ob >> 1) & 31), k = (kk & ~0xC) | ((kk & 4) << 1) | ((kk & 8) >> 1);
;       voff[0][i] = (unsigned)(k * LDP + c); voff[1][i] = (unsigned)(k * LDP + 128 + c); } }
;   typedef __attribute__((address_space(3))) unsigned lds_u32;
;     ...
;   const int NT = U.nt;
;   DDMA(0, 0); DPUB();
;   for (int j = 0; j < NT; j += 2) {
;     DDMA(j + 1, 1); SBAR();
.LBB0_1432:
	s_and_b64 vcc, exec, s[62:63]
	s_cbranch_vccz .LBB0_1404
	v_mov_b32_e32 v8, v210
	v_mov_b64_e32 v[2:3], s[56:57]
	v_readfirstlane_b32 s0, v8
	s_ashr_i32 s3, s0, 6
	s_and_b32 s0, s0, 0x3fffffc0
	s_lshl_b32 s0, s0, 2
	v_and_b32_e32 v234, 31, v8
	s_add_i32 s28, s0, 0
	s_lshl_b32 s60, s3, 5
	v_bfe_u32 v233, v8, 5, 1
	s_add_i32 s28, s28, 0x18000
	v_or_b32_e32 v0, s60, v234
	s_add_i32 s67, 0, 0x10000
	v_mad_i64_i32 v[2:3], s[0:1], v0, s92, v[2:3]
	v_lshlrev_b32_e32 v212, 4, v233
	v_mov_b32_e32 v213, v1
	s_cmp_lg_u32 s67, -1
	v_lshl_add_u64 v[2:3], v[2:3], 0, v[212:213]
	s_cselect_b32 s0, s67, 0
	s_lshl_b32 s29, s3, 11
	global_load_dwordx4 v[162:165], v[2:3], off
	global_load_dwordx4 v[166:169], v[2:3], off offset:32
	global_load_dwordx4 v[170:173], v[2:3], off offset:64
	global_load_dwordx4 v[174:177], v[2:3], off offset:96
	global_load_dwordx4 v[178:181], v[2:3], off offset:128
	global_load_dwordx4 v[182:185], v[2:3], off offset:160
	global_load_dwordx4 v[186:189], v[2:3], off offset:192
	global_load_dwordx4 v[190:193], v[2:3], off offset:224
	s_ashr_i32 s1, s29, 8
	v_lshrrev_b32_e32 v2, 1, v8
	v_and_b32_e32 v9, 63, v8
	v_bfe_u32 v0, v8, 2, 2
	s_and_b32 s3, s1, 0xfffff0
	v_and_b32_e32 v2, 8, v2
	s_waitcnt vmcnt(0)
	v_lshlrev_b32_e32 v12, 4, v9
	s_lshr_b32 s1, s1, 1
	v_or3_b32 v0, v2, v0, s3
	v_and_or_b32 v0, s1, 4, v0
	v_or_b32_e32 v5, 0x400, v12
	v_mul_i32_i24_e32 v13, 0x1800, v0
	v_or_b32_e32 v0, s29, v12
	v_or_b32_e32 v4, s29, v5
	v_and_b32_e32 v3, 15, v8
	v_ashrrev_i32_e32 v0, 8, v0
	v_ashrrev_i32_e32 v4, 8, v4
	v_bitop3_b32 v2, v0, v3, 15 bitop3:0x6c
	v_bitop3_b32 v3, v4, v3, 15 bitop3:0x6c
	v_mul_i32_i24_e32 v4, 0x1800, v4
	v_lshlrev_b32_e32 v10, 3, v9
	v_mul_i32_i24_e32 v0, 0x1800, v0
	v_lshl_or_b32 v4, v3, 3, v4
	v_lshrrev_b32_e32 v3, 4, v5
	v_and_b32_e32 v11, 24, v10
	v_lshl_or_b32 v0, v2, 3, v0
	v_and_b32_e32 v14, 32, v8
	v_and_b32_e32 v3, 0x60, v3
	s_add_i32 s61, s67, s29
	v_or3_b32 v2, v11, v14, v13
	v_or3_b32 v6, v11, v3, v13
	v_lshl_add_u64 v[214:215], v[0:1], 1, s[24:25]
	s_mov_b32 m0, s61
	v_mov_b32_e32 v3, v1
	s_add_i32 s62, s29, 0
	global_load_lds_dwordx4 v[214:215], off
	v_lshl_add_u64 v[2:3], v[2:3], 1, s[22:23]
	s_mov_b32 m0, s62
	s_add_i32 s63, s62, 0x4000
	s_or_b32 s66, s29, 0x400
	global_load_lds_dwordx4 v[2:3], off
	v_lshl_add_u64 v[2:3], v[2:3], 0, s[8:9]
	s_mov_b32 m0, s63
	v_mov_b32_e32 v5, v1
	s_add_i32 s67, s67, s66
	global_load_lds_dwordx4 v[2:3], off
	v_lshl_add_u64 v[216:217], v[4:5], 1, s[24:25]
	s_mov_b32 m0, s67
	v_mov_b32_e32 v7, v1
	s_add_i32 s68, s62, 0x400
	global_load_lds_dwordx4 v[216:217], off
	v_lshl_add_u64 v[2:3], v[6:7], 1, s[22:23]
	s_mov_b32 m0, s68
	s_add_i32 s69, s62, 0x4400
	global_load_lds_dwordx4 v[2:3], off
	v_lshl_add_u64 v[2:3], v[2:3], 0, s[8:9]
	s_mov_b32 m0, s69
	v_lshlrev_b32_e32 v0, 1, v8
	global_load_lds_dwordx4 v[2:3], off
	v_and_b32_e32 v0, 32, v0
	v_and_or_b32 v0, v12, s93, v0
	v_and_b32_e32 v2, 0x100, v10
	s_cmp_lg_u32 0, -1
	v_or3_b32 v0, v0, v2, v11
	s_cselect_b32 s3, 0, 0
	v_add_u32_e32 v213, s3, v0
	s_add_i32 s3, s3, 0x8000
	v_add_u32_e32 v244, s3, v0
	v_or3_b32 v0, v13, v14, v11
	s_movk_i32 s3, 0x60
	v_bitop3_b32 v3, v233, v8, 15 bitop3:0x78
	v_lshl_add_u64 v[218:219], v[0:1], 1, s[22:23]
	v_bitop3_b32 v0, v9, s3, 64 bitop3:0xc8
	v_lshlrev_b32_e32 v2, 8, v234
	v_lshlrev_b32_e32 v3, 4, v3
	v_or3_b32 v0, v13, v0, v11
	v_mov_b32_e32 v14, v1
	v_mov_b32_e32 v15, v1
	v_add3_u32 v235, v2, s0, v3
	s_waitcnt vmcnt(0)
	v_cmp_gt_u32_e64 s[0:1], 32, v9
	v_lshl_add_u64 v[220:221], v[0:1], 1, s[22:23]
	v_mov_b32_e32 v0, v1
	v_mov_b32_e32 v2, v1
	v_mov_b32_e32 v3, v1
	v_mov_b32_e32 v4, v1
	v_mov_b32_e32 v6, v1
	v_mov_b32_e32 v8, v1
	v_mov_b32_e32 v9, v1
	v_mov_b32_e32 v10, v1
	v_mov_b32_e32 v11, v1
	v_mov_b32_e32 v12, v1
	v_mov_b32_e32 v13, v1
	v_mov_b64_e32 v[128:129], v[14:15]
	v_mov_b64_e32 v[112:113], v[14:15]
	v_mov_b64_e32 v[96:97], v[14:15]
	v_mov_b64_e32 v[80:81], v[14:15]
	v_mov_b64_e32 v[64:65], v[14:15]
	v_mov_b64_e32 v[48:49], v[14:15]
	v_mov_b64_e32 v[32:33], v[14:15]
	v_mov_b64_e32 v[126:127], v[12:13]
	v_mov_b64_e32 v[124:125], v[10:11]
	v_mov_b64_e32 v[122:123], v[8:9]
	v_mov_b64_e32 v[120:121], v[6:7]
	v_mov_b64_e32 v[118:119], v[4:5]
	v_mov_b64_e32 v[116:117], v[2:3]
	v_mov_b64_e32 v[114:115], v[0:1]
	v_mov_b64_e32 v[110:111], v[12:13]
	v_mov_b64_e32 v[108:109], v[10:11]
	v_mov_b64_e32 v[106:107], v[8:9]
	v_mov_b64_e32 v[104:105], v[6:7]
	v_mov_b64_e32 v[102:103], v[4:5]
	v_mov_b64_e32 v[100:101], v[2:3]
	v_mov_b64_e32 v[98:99], v[0:1]
	v_mov_b64_e32 v[94:95], v[12:13]
	v_mov_b64_e32 v[92:93], v[10:11]
	v_mov_b64_e32 v[90:91], v[8:9]
	v_mov_b64_e32 v[88:89], v[6:7]
	v_mov_b64_e32 v[86:87], v[4:5]
	v_mov_b64_e32 v[84:85], v[2:3]
	v_mov_b64_e32 v[82:83], v[0:1]
	v_mov_b64_e32 v[78:79], v[12:13]
	v_mov_b64_e32 v[76:77], v[10:11]
	v_mov_b64_e32 v[74:75], v[8:9]
	v_mov_b64_e32 v[72:73], v[6:7]
	v_mov_b64_e32 v[70:71], v[4:5]
	v_mov_b64_e32 v[68:69], v[2:3]
	v_mov_b64_e32 v[66:67], v[0:1]
	v_mov_b64_e32 v[62:63], v[12:13]
	v_mov_b64_e32 v[60:61], v[10:11]
	v_mov_b64_e32 v[58:59], v[8:9]
	v_mov_b64_e32 v[56:57], v[6:7]
	v_mov_b64_e32 v[54:55], v[4:5]
	v_mov_b64_e32 v[52:53], v[2:3]
	v_mov_b64_e32 v[50:51], v[0:1]
	v_mov_b64_e32 v[46:47], v[12:13]
	v_mov_b64_e32 v[44:45], v[10:11]
	v_mov_b64_e32 v[42:43], v[8:9]
	v_mov_b64_e32 v[40:41], v[6:7]
	v_mov_b64_e32 v[38:39], v[4:5]
	v_mov_b64_e32 v[36:37], v[2:3]
	v_mov_b64_e32 v[34:35], v[0:1]
	v_mov_b64_e32 v[30:31], v[12:13]
	v_mov_b64_e32 v[28:29], v[10:11]
	v_mov_b64_e32 v[26:27], v[8:9]
	v_mov_b64_e32 v[24:25], v[6:7]
	v_mov_b64_e32 v[22:23], v[4:5]
	v_mov_b64_e32 v[20:21], v[2:3]
	v_mov_b64_e32 v[18:19], v[0:1]
	v_mov_b64_e32 v[16:17], v[14:15]
	s_mov_b32 s80, 2
	v_xor_b32_e32 v236, 32, v235
	v_xor_b32_e32 v238, 64, v235
	v_xor_b32_e32 v239, 0x60, v235
	v_xor_b32_e32 v240, 0x80, v235
	v_xor_b32_e32 v241, 0xa0, v235
	v_xor_b32_e32 v242, 0xc0, v235
	v_xor_b32_e32 v243, 0xe0, v235
	v_lshl_add_u32 v237, v234, 2, s28
	v_mov_b32_e32 v245, 0
	v_mov_b32_e32 v246, 0xf149f2ca
	s_mov_b64 s[22:23], 0
	v_mov_b64_e32 v[14:15], v[12:13]
	v_mov_b64_e32 v[12:13], v[10:11]
	v_mov_b64_e32 v[10:11], v[8:9]
	v_mov_b64_e32 v[8:9], v[6:7]
	v_mov_b64_e32 v[6:7], v[4:5]
	v_mov_b64_e32 v[4:5], v[2:3]
	v_mov_b64_e32 v[2:3], v[0:1]
	s_waitcnt vmcnt(0) lgkmcnt(0)
	s_barrier
	ds_read_b128 v[194:197], v235 offset:0
	ds_read_b128 v[198:201], v236 offset:0
	ds_read_b128 v[202:205], v238 offset:0
	ds_read_b128 v[206:209], v239 offset:0
	s_cmp_lt_u32 s29, 0x2000
	s_cbranch_scc1 .Lda_l1_lead_in
	v_lshl_add_u64 v[232:233], v[214:215], 0, s[10:11]
	s_add_i32 m0, s94, s29
	s_nop 0
	global_load_lds_dwordx4 v[232:233], off
	v_lshl_add_u64 v[232:233], v[216:217], 0, s[10:11]
	s_add_i32 m0, s94, s66
	s_nop 0
	global_load_lds_dwordx4 v[232:233], off
	s_barrier

; __device__ __forceinline__ void partialSM(f32x16& p0, f32x16& p1, float& m_reg, float& mn, float& alpha) {
;     ...
;   float mnC = -mn * C;
; #pragma unroll
;   for (int r = 0; r < 16; ++r) p0[r] = fmaf(p0[r], C, mnC);
; #pragma unroll
;   for (int r = 0; r < 16; ++r) p1[r] = fmaf(p1[r], C, mnC);
; #pragma unroll
;   for (int r = 0; r < 16; ++r) p0[r] = __builtin_amdgcn_exp2f(p0[r]);
; }
; __device__ __forceinline__ void finishSM(f32x16& p0, f32x16& p1, float alpha, float& l_reg, bf16x8& pa0, bf16x8& pa1, bf16x8& pa2, bf16x8& pa3) {
; #pragma unroll
;   for (int r = 0; r < 16; ++r) p1[r] = __builtin_amdgcn_exp2f(p1[r]);
;   float ps = 0;
; #pragma unroll
;   for (int r = 0; r < 16; ++r) ps += p0[r];
; #pragma unroll
;   for (int r = 0; r < 16; ++r) ps += p1[r];
;   { auto rr = __builtin_amdgcn_permlane32_swap(__float_as_uint(ps), __float_as_uint(ps), false, false);
;     ps = __uint_as_float(rr[0]) + __uint_as_float(rr[1]); }
;   l_reg = l_reg * alpha + ps;
;     ...
;   PK4(p0, 0, pa0); PK4(p0, 8, pa1); PK4(p1, 0, pa2); PK4(p1, 8, pa3);
;     ...
; }
; template <int I> __device__ __forceinline__ void pv_rd(int vb, s16x4& l, s16x4& h) {
;   constexpr int D0 = I >> 2, KS = I & 3, IMG = (D0 >> 2) * 16384, DD = D0 & 3;
;   l = tr_read<IMG + v_rd_off(DD, KS, 0)>(vb); h = tr_read<IMG + v_rd_off(DD, KS, 1)>(vb);
; }
; template <int I> __device__ __forceinline__ void pv_step(f32x16* o, int vb, const bf16x8 (&pa)[4], s16x4 (&l)[3], s16x4 (&h)[3]) {
;   if constexpr (I + 2 < 32) pv_rd<(I + 2 < 32 ? I + 2 : 0)>(vb, l[(I + 2) % 3], h[(I + 2) % 3]);
;   if constexpr (I + 2 < 32) asm volatile("s_waitcnt lgkmcnt(4)" ::: "memory"); else if constexpr (I + 1 < 32) asm volatile("s_waitcnt lgkmcnt(2)" ::: "memory"); else asm volatile("s_waitcnt lgkmcnt(0)" ::: "memory");
;   SBAR();
;   const s16x4 L = l[I % 3], H = h[I % 3];
;   o[I >> 2] = __builtin_amdgcn_mfma_f32_32x32x16_bf16(pa[I & 3], (bf16x8){L[0], L[1], L[2], L[3], H[0], H[1], H[2], H[3]}, o[I >> 2], 0, 0, 0);
;   SBAR();
;   if constexpr (I + 1 < 32) pv_step<(I + 1 < 32 ? I + 1 : 31)>(o, vb, pa, l, h);
; }
; __device__ __forceinline__ void pv_all_rolling(f32x16* o, int vb, bf16x8 pa0, bf16x8 pa1, bf16x8 pa2, bf16x8 pa3) {
;   const bf16x8 pa[4] = {pa0, pa1, pa2, pa3}; s16x4 l[3], h[3];
;   asm volatile("s_waitcnt lgkmcnt(0)" ::: "memory");
;   pv_rd<0>(vb, l[0], h[0]); pv_rd<1>(vb, l[1], h[1]);
;   pv_step<0>(o, vb, pa, l, h);
.LBB0_1435:
	v_cndmask_b32_e64 v246, v223, v246, s[6:7]
	v_mul_f32_e32 v194, 0xbe0293ee, v246
	v_fmamk_f32 v146, v146, 0x3e0293ee, v194
	v_fmamk_f32 v147, v147, 0x3e0293ee, v194
	v_fmamk_f32 v148, v148, 0x3e0293ee, v194
	v_fmamk_f32 v149, v149, 0x3e0293ee, v194
	v_fmamk_f32 v150, v150, 0x3e0293ee, v194
	v_fmamk_f32 v151, v151, 0x3e0293ee, v194
	v_fmamk_f32 v152, v152, 0x3e0293ee, v194
	v_fmamk_f32 v153, v153, 0x3e0293ee, v194
	v_fmamk_f32 v154, v154, 0x3e0293ee, v194
	v_fmamk_f32 v155, v155, 0x3e0293ee, v194
	v_fmamk_f32 v156, v156, 0x3e0293ee, v194
	v_fmamk_f32 v157, v157, 0x3e0293ee, v194
	v_fmamk_f32 v158, v158, 0x3e0293ee, v194
	v_fmamk_f32 v159, v159, 0x3e0293ee, v194
	v_fmamk_f32 v160, v160, 0x3e0293ee, v194
	v_fmamk_f32 v161, v161, 0x3e0293ee, v194
	v_fmamk_f32 v130, v130, 0x3e0293ee, v194
	v_fmamk_f32 v131, v131, 0x3e0293ee, v194
	v_fmamk_f32 v132, v132, 0x3e0293ee, v194
	v_fmamk_f32 v133, v133, 0x3e0293ee, v194
	v_fmamk_f32 v134, v134, 0x3e0293ee, v194
	v_fmamk_f32 v135, v135, 0x3e0293ee, v194
	v_fmamk_f32 v136, v136, 0x3e0293ee, v194
	v_fmamk_f32 v137, v137, 0x3e0293ee, v194
	v_fmamk_f32 v138, v138, 0x3e0293ee, v194
	v_fmamk_f32 v139, v139, 0x3e0293ee, v194
	v_fmamk_f32 v140, v140, 0x3e0293ee, v194
	v_fmamk_f32 v141, v141, 0x3e0293ee, v194
	v_fmamk_f32 v142, v142, 0x3e0293ee, v194
	v_fmamk_f32 v143, v143, 0x3e0293ee, v194
	v_fmamk_f32 v144, v144, 0x3e0293ee, v194
	v_fmac_f32_e32 v194, 0x3e0293ee, v145
	v_exp_f32_e32 v145, v146
	v_exp_f32_e32 v146, v147
	v_exp_f32_e32 v147, v148
	v_exp_f32_e32 v148, v149
	v_exp_f32_e32 v149, v150
	v_exp_f32_e32 v150, v151
	v_exp_f32_e32 v151, v152
	v_exp_f32_e32 v152, v153
	v_exp_f32_e32 v153, v154
	v_exp_f32_e32 v154, v155
	v_exp_f32_e32 v155, v156
	v_exp_f32_e32 v156, v157
	v_exp_f32_e32 v157, v158
	v_exp_f32_e32 v158, v159
	v_exp_f32_e32 v159, v160
	v_exp_f32_e32 v160, v161
	v_add_f32_e32 v161, v247, v248
	v_fmac_f32_e32 v161, v245, v0
	v_exp_f32_e32 v0, v130
	v_add_f32_e32 v130, 0, v145
	v_add_f32_e32 v130, v146, v130
	v_add_f32_e32 v130, v147, v130
	v_add_f32_e32 v130, v148, v130
	v_add_f32_e32 v130, v149, v130
	v_add_f32_e32 v130, v150, v130
	v_add_f32_e32 v130, v151, v130
	v_add_f32_e32 v130, v152, v130
	v_add_f32_e32 v130, v153, v130
	v_add_f32_e32 v130, v154, v130
	v_add_f32_e32 v130, v155, v130
	v_add_f32_e32 v130, v156, v130
	v_add_f32_e32 v130, v157, v130
	v_exp_f32_e32 v195, v131
	v_add_f32_e32 v130, v158, v130
	v_exp_f32_e32 v196, v132
	v_add_f32_e32 v130, v159, v130
	v_exp_f32_e32 v197, v133
	v_add_f32_e32 v130, v160, v130
	v_exp_f32_e32 v198, v134
	v_add_f32_e32 v130, v0, v130
	v_exp_f32_e32 v199, v135
	v_add_f32_e32 v130, v195, v130
	v_exp_f32_e32 v200, v136
	v_add_f32_e32 v130, v196, v130
	v_exp_f32_e32 v201, v137
	v_add_f32_e32 v130, v197, v130
	v_exp_f32_e32 v202, v138
	v_add_f32_e32 v130, v198, v130
	v_exp_f32_e32 v203, v139
	v_add_f32_e32 v130, v199, v130
	v_exp_f32_e32 v204, v140
	v_add_f32_e32 v130, v200, v130
	v_exp_f32_e32 v205, v141
	v_add_f32_e32 v130, v201, v130
	v_exp_f32_e32 v206, v142
	v_add_f32_e32 v130, v202, v130
	v_exp_f32_e32 v207, v143
	v_add_f32_e32 v130, v203, v130
	v_exp_f32_e32 v208, v144
	v_add_f32_e32 v130, v204, v130
	v_exp_f32_e32 v194, v194
	v_add_f32_e32 v130, v205, v130
	v_add_f32_e32 v130, v206, v130
	v_add_f32_e32 v130, v207, v130
	v_add_f32_e32 v130, v208, v130
	v_add_f32_e32 v130, v194, v130
	v_mov_b32_e32 v131, v130
	s_nop 1
	v_permlane32_swap_b32_e32 v130, v131
	v_add_f32_e32 v245, v130, v131
	v_fmac_f32_e32 v245, v161, v222
	s_waitcnt vmcnt(0)
	s_barrier
	s_setprio 0
	v_cvt_pk_bf16_f32 v130, v145, v146
	v_cvt_pk_bf16_f32 v131, v147, v148
	v_cvt_pk_bf16_f32 v132, v149, v150
	v_cvt_pk_bf16_f32 v133, v151, v152
	v_cvt_pk_bf16_f32 v134, v153, v154
	v_cvt_pk_bf16_f32 v135, v155, v156
	v_cvt_pk_bf16_f32 v136, v157, v158
	v_cvt_pk_bf16_f32 v137, v159, v160
	v_cvt_pk_bf16_f32 v138, v0, v195
	v_cvt_pk_bf16_f32 v139, v196, v197
	v_cvt_pk_bf16_f32 v140, v198, v199
	v_cvt_pk_bf16_f32 v141, v200, v201
	v_cvt_pk_bf16_f32 v142, v202, v203
	v_cvt_pk_bf16_f32 v143, v204, v205
	v_cvt_pk_bf16_f32 v144, v206, v207
	v_cvt_pk_bf16_f32 v145, v208, v194
	s_nop 0
	v_permlane32_swap_b32_e32 v130, v132
	v_permlane32_swap_b32_e32 v131, v133
	v_permlane32_swap_b32_e32 v134, v136
	v_permlane32_swap_b32_e32 v135, v137
	v_permlane32_swap_b32_e32 v138, v140
	v_permlane32_swap_b32_e32 v139, v141
	v_permlane32_swap_b32_e32 v142, v144
	v_permlane32_swap_b32_e32 v143, v145
	s_waitcnt lgkmcnt(0)
	ds_read_b64_tr_b16 v[146:147], v244 offset:0
	ds_read_b64_tr_b16 v[148:149], v244 offset:2048
	ds_read_b64_tr_b16 v[150:151], v244 offset:4096
	ds_read_b64_tr_b16 v[152:153], v244 offset:6144
	ds_read_b64_tr_b16 v[154:155], v244 offset:8192
	ds_read_b64_tr_b16 v[156:157], v244 offset:10240
	ds_read_b64_tr_b16 v[158:159], v244 offset:12288
	ds_read_b64_tr_b16 v[160:161], v244 offset:14336
	v_lshl_add_u64 v[232:233], v[218:219], 0, s[22:23]
	v_lshl_add_u64 v[232:233], v[232:233], 0, s[14:15]
	s_mov_b32 m0, s62
	s_nop 0
	global_load_lds_dwordx4 v[232:233], off
	s_waitcnt lgkmcnt(6)
	s_nop 0
	v_mfma_f32_32x32x16_bf16 v[114:129], v[130:133], v[146:149], v[114:129]
	ds_read_b64_tr_b16 v[146:147], v244 offset:512
	ds_read_b64_tr_b16 v[148:149], v244 offset:2560
	v_lshl_add_u64 v[232:233], v[218:219], 0, s[22:23]
	v_lshl_add_u64 v[232:233], v[232:233], 0, s[16:17]
	s_mov_b32 m0, s63
	s_nop 0
	global_load_lds_dwordx4 v[232:233], off
	s_waitcnt lgkmcnt(6)
	v_mfma_f32_32x32x16_bf16 v[114:129], v[134:137], v[150:153], v[114:129]
	ds_read_b64_tr_b16 v[150:151], v244 offset:4608
	ds_read_b64_tr_b16 v[152:153], v244 offset:6656
	v_lshl_add_u64 v[232:233], v[220:221], 0, s[22:23]
	v_lshl_add_u64 v[232:233], v[232:233], 0, s[14:15]
	s_mov_b32 m0, s68
	s_nop 0
	global_load_lds_dwordx4 v[232:233], off
	s_waitcnt lgkmcnt(6)
; #define SBAR() __builtin_amdgcn_sched_barrier(0)
; #define DPUB() do { asm volatile("s_waitcnt vmcnt(0)" ::: "memory"); __syncthreads(); } while (0)
; #define DTILE(b) do { f32x16 p0 = f32x16{}, p1 = f32x16{}; float mn, al; bf16x8 pa0, pa1, pa2, pa3; \
;     qkt_rolling<(b) * DA_KB>(p0, p1, ka0, qr); partialSM(p0, p1, m_reg, mn, al); DRESC(al); finishSM(p0, p1, al, l_reg, pa0, pa1, pa2, pa3); SBAR(); \
;     pv_all_rolling(o, vb0 + (b) * DA_VB, pa0, pa1, pa2, pa3); } while (0)
; template <int I> __device__ __forceinline__ void pv_rd(int vb, s16x4& l, s16x4& h) {
;   constexpr int D0 = I >> 2, KS = I & 3, IMG = (D0 >> 2) * 16384, DD = D0 & 3;
;   l = tr_read<IMG + v_rd_off(DD, KS, 0)>(vb); h = tr_read<IMG + v_rd_off(DD, KS, 1)>(vb);
; }
; template <int I> __device__ __forceinline__ void pv_step(f32x16* o, int vb, const bf16x8 (&pa)[4], s16x4 (&l)[3], s16x4 (&h)[3]) {
;   if constexpr (I + 2 < 32) pv_rd<(I + 2 < 32 ? I + 2 : 0)>(vb, l[(I + 2) % 3], h[(I + 2) % 3]);
;   if constexpr (I + 2 < 32) asm volatile("s_waitcnt lgkmcnt(4)" ::: "memory"); else if constexpr (I + 1 < 32) asm volatile("s_waitcnt lgkmcnt(2)" ::: "memory"); else asm volatile("s_waitcnt lgkmcnt(0)" ::: "memory");
;   SBAR();
;   const s16x4 L = l[I % 3], H = h[I % 3];
;   o[I >> 2] = __builtin_amdgcn_mfma_f32_32x32x16_bf16(pa[I & 3], (bf16x8){L[0], L[1], L[2], L[3], H[0], H[1], H[2], H[3]}, o[I >> 2], 0, 0, 0);
;   SBAR();
;   if constexpr (I + 1 < 32) pv_step<(I + 1 < 32 ? I + 1 : 31)>(o, vb, pa, l, h);
; }
; __device__ __forceinline__ void pv_all_rolling(f32x16* o, int vb, bf16x8 pa0, bf16x8 pa1, bf16x8 pa2, bf16x8 pa3) {
;   const bf16x8 pa[4] = {pa0, pa1, pa2, pa3}; s16x4 l[3], h[3];
;   asm volatile("s_waitcnt lgkmcnt(0)" ::: "memory");
;   pv_rd<0>(vb, l[0], h[0]); pv_rd<1>(vb, l[1], h[1]);
;   pv_step<0>(o, vb, pa, l, h);
; }
; __device__ __forceinline__ void unit_body_da(const Unit& U, char* lds) {
;     ...
;   for (int j = 0; j < NT; j += 2) {
;     DDMA(j + 1, 1); SBAR();
;     DTILE(0); SBAR(); DPUB();
;     if (j + 2 < NT) DDMA(j + 2, 0); SBAR();
;     DTILE(1); SBAR(); DPUB();
;   }
	v_mfma_f32_32x32x16_bf16 v[114:129], v[138:141], v[154:157], v[114:129]
	ds_read_b64_tr_b16 v[154:155], v244 offset:8704
	ds_read_b64_tr_b16 v[156:157], v244 offset:10752
	v_lshl_add_u64 v[232:233], v[220:221], 0, s[22:23]
	v_lshl_add_u64 v[232:233], v[232:233], 0, s[16:17]
	s_mov_b32 m0, s69
	s_nop 0
	global_load_lds_dwordx4 v[232:233], off
	s_waitcnt lgkmcnt(6)
	v_mfma_f32_32x32x16_bf16 v[114:129], v[142:145], v[158:161], v[114:129]
	ds_read_b64_tr_b16 v[158:159], v244 offset:12800
	ds_read_b64_tr_b16 v[160:161], v244 offset:14848
	s_waitcnt lgkmcnt(6)
	v_mfma_f32_32x32x16_bf16 v[98:113], v[130:133], v[146:149], v[98:113]
	ds_read_b64_tr_b16 v[146:147], v244 offset:1024
	ds_read_b64_tr_b16 v[148:149], v244 offset:3072
	s_waitcnt lgkmcnt(6)
	v_mfma_f32_32x32x16_bf16 v[98:113], v[134:137], v[150:153], v[98:113]
	ds_read_b64_tr_b16 v[150:151], v244 offset:5120
	ds_read_b64_tr_b16 v[152:153], v244 offset:7168
	s_waitcnt lgkmcnt(6)
	v_mfma_f32_32x32x16_bf16 v[98:113], v[138:141], v[154:157], v[98:113]
	ds_read_b64_tr_b16 v[154:155], v244 offset:9216
	ds_read_b64_tr_b16 v[156:157], v244 offset:11264
	s_waitcnt lgkmcnt(6)
	v_mfma_f32_32x32x16_bf16 v[98:113], v[142:145], v[158:161], v[98:113]
	ds_read_b64_tr_b16 v[158:159], v244 offset:13312
	ds_read_b64_tr_b16 v[160:161], v244 offset:15360
	s_cmp_lt_u32 s29, 0x2000
	s_cbranch_scc1 .Lda_l1_s1_nolk
	v_lshl_add_u64 v[232:233], v[224:225], 0, s[14:15]
	v_lshl_add_u64 v[232:233], v[232:233], 0, s[10:11]
	s_add_i32 m0, s94, s29
	s_nop 0
	global_load_lds_dwordx4 v[232:233], off
	v_lshl_add_u64 v[232:233], v[228:229], 0, s[14:15]
	v_lshl_add_u64 v[232:233], v[232:233], 0, s[10:11]
	s_add_i32 m0, s94, s66
	s_nop 0
	global_load_lds_dwordx4 v[232:233], off
.Lda_l1_s1_nolk:
	s_waitcnt lgkmcnt(6)
	v_mfma_f32_32x32x16_bf16 v[82:97], v[130:133], v[146:149], v[82:97]
	ds_read_b64_tr_b16 v[146:147], v244 offset:1536
	ds_read_b64_tr_b16 v[148:149], v244 offset:3584
	s_waitcnt lgkmcnt(6)
	v_mfma_f32_32x32x16_bf16 v[82:97], v[134:137], v[150:153], v[82:97]
	ds_read_b64_tr_b16 v[150:151], v244 offset:5632
	ds_read_b64_tr_b16 v[152:153], v244 offset:7680
	s_waitcnt lgkmcnt(6)
	v_mfma_f32_32x32x16_bf16 v[82:97], v[138:141], v[154:157], v[82:97]
	ds_read_b64_tr_b16 v[154:155], v244 offset:9728
	ds_read_b64_tr_b16 v[156:157], v244 offset:11776
	s_waitcnt lgkmcnt(6)
	v_mfma_f32_32x32x16_bf16 v[82:97], v[142:145], v[158:161], v[82:97]
	ds_read_b64_tr_b16 v[158:159], v244 offset:13824
	ds_read_b64_tr_b16 v[160:161], v244 offset:15872
	s_waitcnt lgkmcnt(6)
	v_mfma_f32_32x32x16_bf16 v[66:81], v[130:133], v[146:149], v[66:81]
	ds_read_b64_tr_b16 v[146:147], v244 offset:16384
	ds_read_b64_tr_b16 v[148:149], v244 offset:18432
	s_waitcnt lgkmcnt(6)
	v_mfma_f32_32x32x16_bf16 v[66:81], v[134:137], v[150:153], v[66:81]
	ds_read_b64_tr_b16 v[150:151], v244 offset:20480
	ds_read_b64_tr_b16 v[152:153], v244 offset:22528
	s_waitcnt lgkmcnt(6)
	v_mfma_f32_32x32x16_bf16 v[66:81], v[138:141], v[154:157], v[66:81]
	ds_read_b64_tr_b16 v[154:155], v244 offset:24576
	ds_read_b64_tr_b16 v[156:157], v244 offset:26624
	s_waitcnt lgkmcnt(6)
	v_mfma_f32_32x32x16_bf16 v[66:81], v[142:145], v[158:161], v[66:81]
	ds_read_b64_tr_b16 v[158:159], v244 offset:28672
	ds_read_b64_tr_b16 v[160:161], v244 offset:30720
	s_waitcnt lgkmcnt(6)
	v_mfma_f32_32x32x16_bf16 v[50:65], v[130:133], v[146:149], v[50:65]
	ds_read_b64_tr_b16 v[146:147], v244 offset:16896
	ds_read_b64_tr_b16 v[148:149], v244 offset:18944
	s_waitcnt lgkmcnt(6)
	v_mfma_f32_32x32x16_bf16 v[50:65], v[134:137], v[150:153], v[50:65]
	ds_read_b64_tr_b16 v[150:151], v244 offset:20992
	ds_read_b64_tr_b16 v[152:153], v244 offset:23040
	s_waitcnt lgkmcnt(6)
	v_mfma_f32_32x32x16_bf16 v[50:65], v[138:141], v[154:157], v[50:65]
	ds_read_b64_tr_b16 v[154:155], v244 offset:25088
	ds_read_b64_tr_b16 v[156:157], v244 offset:27136
	s_waitcnt lgkmcnt(6)
	v_mfma_f32_32x32x16_bf16 v[50:65], v[142:145], v[158:161], v[50:65]
	ds_read_b64_tr_b16 v[158:159], v244 offset:29184
	ds_read_b64_tr_b16 v[160:161], v244 offset:31232
	s_waitcnt lgkmcnt(6)
	v_mfma_f32_32x32x16_bf16 v[34:49], v[130:133], v[146:149], v[34:49]
	ds_read_b64_tr_b16 v[146:147], v244 offset:17408
	ds_read_b64_tr_b16 v[148:149], v244 offset:19456
	s_waitcnt lgkmcnt(6)
	v_mfma_f32_32x32x16_bf16 v[34:49], v[134:137], v[150:153], v[34:49]
	ds_read_b64_tr_b16 v[150:151], v244 offset:21504
	ds_read_b64_tr_b16 v[152:153], v244 offset:23552
	s_waitcnt lgkmcnt(6)
	v_mfma_f32_32x32x16_bf16 v[34:49], v[138:141], v[154:157], v[34:49]
	ds_read_b64_tr_b16 v[154:155], v244 offset:25600
	ds_read_b64_tr_b16 v[156:157], v244 offset:27648
	s_waitcnt lgkmcnt(6)
	v_mfma_f32_32x32x16_bf16 v[34:49], v[142:145], v[158:161], v[34:49]
	ds_read_b64_tr_b16 v[158:159], v244 offset:29696
	ds_read_b64_tr_b16 v[160:161], v244 offset:31744
	s_waitcnt lgkmcnt(6)
	v_mfma_f32_32x32x16_bf16 v[18:33], v[130:133], v[146:149], v[18:33]
	ds_read_b64_tr_b16 v[146:147], v244 offset:17920
	ds_read_b64_tr_b16 v[148:149], v244 offset:19968
	s_waitcnt lgkmcnt(6)
	v_mfma_f32_32x32x16_bf16 v[18:33], v[134:137], v[150:153], v[18:33]
	ds_read_b64_tr_b16 v[150:151], v244 offset:22016
	ds_read_b64_tr_b16 v[152:153], v244 offset:24064
	s_waitcnt lgkmcnt(6)
	v_mfma_f32_32x32x16_bf16 v[18:33], v[138:141], v[154:157], v[18:33]
	ds_read_b64_tr_b16 v[154:155], v244 offset:26112
	ds_read_b64_tr_b16 v[156:157], v244 offset:28160
	s_waitcnt lgkmcnt(6)
	v_mfma_f32_32x32x16_bf16 v[18:33], v[142:145], v[158:161], v[18:33]
	ds_read_b64_tr_b16 v[158:159], v244 offset:30208
	ds_read_b64_tr_b16 v[160:161], v244 offset:32256
	ds_read_b128 v[194:197], v235 offset:0
	ds_read_b128 v[198:201], v236 offset:0
	ds_read_b128 v[202:205], v238 offset:0
	ds_read_b128 v[206:209], v239 offset:0
	s_waitcnt lgkmcnt(10)
	v_mfma_f32_32x32x16_bf16 v[2:17], v[130:133], v[146:149], v[2:17]
	s_waitcnt lgkmcnt(8)
	v_mfma_f32_32x32x16_bf16 v[2:17], v[134:137], v[150:153], v[2:17]
	s_waitcnt lgkmcnt(6)
	v_mfma_f32_32x32x16_bf16 v[2:17], v[138:141], v[154:157], v[2:17]
	s_waitcnt lgkmcnt(4)
	v_mfma_f32_32x32x16_bf16 v[2:17], v[142:145], v[158:161], v[2:17]
	s_waitcnt vmcnt(0)
	s_add_u32 s22, s22, 0x180000
	s_addc_u32 s23, s23, 0
	s_add_i32 s80, s80, 2
	s_and_b64 vcc, exec, s[24:25]
	s_waitcnt vmcnt(0) lgkmcnt(0)
	s_barrier
	s_cbranch_vccnz .LBB0_1445
; #define SBAR() __builtin_amdgcn_sched_barrier(0)
; __device__ __forceinline__ void partialSM(f32x16& p0, f32x16& p1, float& m_reg, float& mn, float& alpha) {
;   constexpr float C = SCALE * 1.4426950408889634f;
;   float pmax = p0[0];
; #pragma unroll
;   for (int r = 1; r < 16; ++r) pmax = fmaxf(pmax, p0[r]);
; #pragma unroll
;   for (int r = 0; r < 16; ++r) pmax = fmaxf(pmax, p1[r]);
;   { auto rr = __builtin_amdgcn_permlane32_swap(__float_as_uint(pmax), __float_as_uint(pmax), false, false);
;     pmax = fmaxf(__uint_as_float(rr[0]), __uint_as_float(rr[1])); }
;   if (__builtin_expect(__all(pmax - m_reg <= THR / SCALE), 1)) { mn = m_reg; alpha = 1.f; }
; template <int OFF> __device__ __forceinline__ bf16x8 k_read(int a) { bf16x8 r; asm volatile("ds_read_b128 %0, %1 offset:%2" : "=&v"(r) : "v"(a), "i"(OFF) : "memory"); return r; }
; template <int BUFOFF, int D0> __device__ __forceinline__ void qk_step(f32x16& p0, f32x16& p1, int ka0, const bf16x8 (&qr)[8], bf16x8 (&k0)[2], bf16x8 (&k1)[2]) {
;   if constexpr (D0 + 1 < 8) { const int a_ = ka0 ^ ((D0 + 1) << 5); k0[(D0 + 1) & 1] = k_read<BUFOFF>(a_); k1[(D0 + 1) & 1] = k_read<BUFOFF + 8192>(a_); }
;   if constexpr (D0 + 1 < 8) asm volatile("s_waitcnt lgkmcnt(2)" ::: "memory"); else asm volatile("s_waitcnt lgkmcnt(0)" ::: "memory");
;   SBAR();
;   p0 = __builtin_amdgcn_mfma_f32_32x32x16_bf16(k0[D0 & 1], qr[D0], p0, 0, 0, 0);
;   p1 = __builtin_amdgcn_mfma_f32_32x32x16_bf16(k1[D0 & 1], qr[D0], p1, 0, 0, 0);
;   SBAR();
;   if constexpr (D0 + 1 < 8) qk_step<BUFOFF, (D0 + 1 < 8 ? D0 + 1 : 7)>(p0, p1, ka0, qr, k0, k1);
; }
; template <int BUFOFF> __device__ __forceinline__ void qkt_rolling(f32x16& p0, f32x16& p1, int ka0, const bf16x8 (&qr)[8]) {
;   bf16x8 k0[2], k1[2];
;   asm volatile("s_waitcnt lgkmcnt(0)" ::: "memory");
;   k0[0] = k_read<BUFOFF>(ka0); k1[0] = k_read<BUFOFF + 8192>(ka0);
;   qk_step<BUFOFF, 0>(p0, p1, ka0, qr, k0, k1);
; }
.LBB0_1436:
	s_setprio 1
	v_lshl_add_u64 v[224:225], v[214:215], 0, s[22:23]
	v_lshl_add_u64 v[228:229], v[216:217], 0, s[22:23]
	s_waitcnt lgkmcnt(0)
	ds_read_b128 v[130:133], v240 offset:0
	ds_read_b128 v[134:137], v241 offset:0
	ds_read_b128 v[138:141], v242 offset:0
	ds_read_b128 v[142:145], v243 offset:0
	s_cmp_lt_u32 s29, 0x2000
	s_cbranch_scc0 .Lda_l1_s0_nok
	v_lshl_add_u64 v[232:233], v[224:225], 0, s[10:11]
	s_add_i32 m0, s94, s29
	s_nop 0
	global_load_lds_dwordx4 v[232:233], off
	v_lshl_add_u64 v[232:233], v[228:229], 0, s[10:11]
	s_add_i32 m0, s94, s66
	s_nop 0
	global_load_lds_dwordx4 v[232:233], off
.Lda_l1_s0_nok:
	s_waitcnt lgkmcnt(7)
	s_nop 0
	v_mfma_f32_32x32x16_bf16 v[146:161], v[194:197], v[162:165], 0
	ds_read_b128 v[194:197], v235 offset:8192
	s_waitcnt lgkmcnt(7)
	v_mfma_f32_32x32x16_bf16 v[146:161], v[198:201], v[166:169], v[146:161]
	ds_read_b128 v[198:201], v236 offset:8192
	s_waitcnt lgkmcnt(7)
	v_mfma_f32_32x32x16_bf16 v[146:161], v[202:205], v[170:173], v[146:161]
	ds_read_b128 v[202:205], v238 offset:8192
	s_waitcnt lgkmcnt(7)
	v_mfma_f32_32x32x16_bf16 v[146:161], v[206:209], v[174:177], v[146:161]
	ds_read_b128 v[206:209], v239 offset:8192
	s_waitcnt lgkmcnt(7)
	v_mfma_f32_32x32x16_bf16 v[146:161], v[130:133], v[178:181], v[146:161]
	s_waitcnt lgkmcnt(6)
	v_mfma_f32_32x32x16_bf16 v[146:161], v[134:137], v[182:185], v[146:161]
	s_waitcnt lgkmcnt(5)
	v_mfma_f32_32x32x16_bf16 v[146:161], v[138:141], v[186:189], v[146:161]
	s_waitcnt lgkmcnt(4)
	v_mfma_f32_32x32x16_bf16 v[146:161], v[142:145], v[190:193], v[146:161]
	s_waitcnt lgkmcnt(3)
	v_mfma_f32_32x32x16_bf16 v[130:145], v[194:197], v[162:165], 0
	ds_read_b128 v[194:197], v240 offset:8192
	s_waitcnt lgkmcnt(3)
	v_mfma_f32_32x32x16_bf16 v[130:145], v[198:201], v[166:169], v[130:145]
	ds_read_b128 v[198:201], v241 offset:8192
	s_waitcnt lgkmcnt(3)
	v_mfma_f32_32x32x16_bf16 v[130:145], v[202:205], v[170:173], v[130:145]
	ds_read_b128 v[202:205], v242 offset:8192
	s_waitcnt lgkmcnt(3)
	v_mfma_f32_32x32x16_bf16 v[130:145], v[206:209], v[174:177], v[130:145]
	ds_read_b128 v[206:209], v243 offset:8192
	s_waitcnt lgkmcnt(3)
	v_mfma_f32_32x32x16_bf16 v[130:145], v[194:197], v[178:181], v[130:145]
	s_waitcnt lgkmcnt(2)
	v_mfma_f32_32x32x16_bf16 v[130:145], v[198:201], v[182:185], v[130:145]
	s_waitcnt lgkmcnt(1)
	v_mfma_f32_32x32x16_bf16 v[130:145], v[202:205], v[186:189], v[130:145]
	s_waitcnt lgkmcnt(0)
	v_mfma_f32_32x32x16_bf16 v[130:145], v[206:209], v[190:193], v[130:145]
	s_setprio 0
	v_max3_f32 v0, v146, v147, v148
	v_max3_f32 v194, v154, v155, v156
	v_max3_f32 v0, v0, v149, v150
	v_max3_f32 v194, v194, v157, v158
	v_max3_f32 v0, v0, v151, v152
	v_max3_f32 v194, v194, v159, v160
	v_max_f32_e32 v0, v0, v153
	v_max_f32_e32 v194, v194, v161
	s_nop 4
	v_max3_f32 v196, v130, v131, v132
	v_max3_f32 v197, v138, v139, v140
	v_max3_f32 v196, v196, v133, v134
	v_max3_f32 v197, v197, v141, v142
	v_max3_f32 v196, v196, v135, v136
	v_max3_f32 v197, v197, v143, v144
	v_max_f32_e32 v196, v196, v137
	v_max_f32_e32 v197, v197, v145
	v_max3_f32 v0, v0, v194, v196
	v_max_f32_e32 v0, v0, v197
	v_mov_b32_e32 v194, v0
	s_nop 1
	v_permlane32_swap_b32_e32 v0, v194
	v_max_f32_e32 v0, v0, v194
	v_sub_f32_e32 v194, v0, v246
	v_cmp_ge_f32_e32 vcc, s95, v194
	s_cmp_eq_u64 vcc, exec
	s_cbranch_scc0 .Lda_slow_l1_1
	s_mov_b64 s[6:7], -1
	v_mov_b32_e32 v0, 1.0
	s_branch .LBB0_1440

; __device__ __forceinline__ void partialSM(f32x16& p0, f32x16& p1, float& m_reg, float& mn, float& alpha) {
;     ...
;   float mnC = -mn * C;
; #pragma unroll
;   for (int r = 0; r < 16; ++r) p0[r] = fmaf(p0[r], C, mnC);
; #pragma unroll
;   for (int r = 0; r < 16; ++r) p1[r] = fmaf(p1[r], C, mnC);
; #pragma unroll
;   for (int r = 0; r < 16; ++r) p0[r] = __builtin_amdgcn_exp2f(p0[r]);
; }
; __device__ __forceinline__ void finishSM(f32x16& p0, f32x16& p1, float alpha, float& l_reg, bf16x8& pa0, bf16x8& pa1, bf16x8& pa2, bf16x8& pa3) {
; #pragma unroll
;   for (int r = 0; r < 16; ++r) p1[r] = __builtin_amdgcn_exp2f(p1[r]);
;   float ps = 0;
; #pragma unroll
;   for (int r = 0; r < 16; ++r) ps += p0[r];
; #pragma unroll
;   for (int r = 0; r < 16; ++r) ps += p1[r];
;   { auto rr = __builtin_amdgcn_permlane32_swap(__float_as_uint(ps), __float_as_uint(ps), false, false);
;     ps = __uint_as_float(rr[0]) + __uint_as_float(rr[1]); }
;   l_reg = l_reg * alpha + ps;
;     ...
;   PK4(p0, 0, pa0); PK4(p0, 8, pa1); PK4(p1, 0, pa2); PK4(p1, 8, pa3);
;     ...
; }
; template <int I> __device__ __forceinline__ void pv_rd(int vb, s16x4& l, s16x4& h) {
;   constexpr int D0 = I >> 2, KS = I & 3, IMG = (D0 >> 2) * 16384, DD = D0 & 3;
;   l = tr_read<IMG + v_rd_off(DD, KS, 0)>(vb); h = tr_read<IMG + v_rd_off(DD, KS, 1)>(vb);
; }
; template <int I> __device__ __forceinline__ void pv_step(f32x16* o, int vb, const bf16x8 (&pa)[4], s16x4 (&l)[3], s16x4 (&h)[3]) {
;   if constexpr (I + 2 < 32) pv_rd<(I + 2 < 32 ? I + 2 : 0)>(vb, l[(I + 2) % 3], h[(I + 2) % 3]);
;   if constexpr (I + 2 < 32) asm volatile("s_waitcnt lgkmcnt(4)" ::: "memory"); else if constexpr (I + 1 < 32) asm volatile("s_waitcnt lgkmcnt(2)" ::: "memory"); else asm volatile("s_waitcnt lgkmcnt(0)" ::: "memory");
;   SBAR();
;   const s16x4 L = l[I % 3], H = h[I % 3];
;   o[I >> 2] = __builtin_amdgcn_mfma_f32_32x32x16_bf16(pa[I & 3], (bf16x8){L[0], L[1], L[2], L[3], H[0], H[1], H[2], H[3]}, o[I >> 2], 0, 0, 0);
;   SBAR();
;   if constexpr (I + 1 < 32) pv_step<(I + 1 < 32 ? I + 1 : 31)>(o, vb, pa, l, h);
; }
; __device__ __forceinline__ void pv_all_rolling(f32x16* o, int vb, bf16x8 pa0, bf16x8 pa1, bf16x8 pa2, bf16x8 pa3) {
;   const bf16x8 pa[4] = {pa0, pa1, pa2, pa3}; s16x4 l[3], h[3];
;   asm volatile("s_waitcnt lgkmcnt(0)" ::: "memory");
;   pv_rd<0>(vb, l[0], h[0]); pv_rd<1>(vb, l[1], h[1]);
;   pv_step<0>(o, vb, pa, l, h);
.LBB0_1440:
	v_cndmask_b32_e64 v246, v247, v246, s[6:7]
	v_mul_f32_e32 v194, 0xbe0293ee, v246
	v_fmamk_f32 v146, v146, 0x3e0293ee, v194
	v_fmamk_f32 v147, v147, 0x3e0293ee, v194
	v_fmamk_f32 v148, v148, 0x3e0293ee, v194
	v_fmamk_f32 v149, v149, 0x3e0293ee, v194
	v_fmamk_f32 v150, v150, 0x3e0293ee, v194
	v_fmamk_f32 v151, v151, 0x3e0293ee, v194
	v_fmamk_f32 v152, v152, 0x3e0293ee, v194
	v_fmamk_f32 v153, v153, 0x3e0293ee, v194
	v_fmamk_f32 v154, v154, 0x3e0293ee, v194
	v_fmamk_f32 v155, v155, 0x3e0293ee, v194
	v_fmamk_f32 v156, v156, 0x3e0293ee, v194
	v_fmamk_f32 v157, v157, 0x3e0293ee, v194
	v_fmamk_f32 v158, v158, 0x3e0293ee, v194
	v_fmamk_f32 v159, v159, 0x3e0293ee, v194
	v_fmamk_f32 v160, v160, 0x3e0293ee, v194
	v_fmamk_f32 v161, v161, 0x3e0293ee, v194
	v_fmamk_f32 v130, v130, 0x3e0293ee, v194
	v_fmamk_f32 v131, v131, 0x3e0293ee, v194
	v_fmamk_f32 v132, v132, 0x3e0293ee, v194
	v_fmamk_f32 v133, v133, 0x3e0293ee, v194
	v_fmamk_f32 v134, v134, 0x3e0293ee, v194
	v_fmamk_f32 v135, v135, 0x3e0293ee, v194
	v_fmamk_f32 v136, v136, 0x3e0293ee, v194
	v_fmamk_f32 v137, v137, 0x3e0293ee, v194
	v_fmamk_f32 v138, v138, 0x3e0293ee, v194
	v_fmamk_f32 v139, v139, 0x3e0293ee, v194
	v_fmamk_f32 v140, v140, 0x3e0293ee, v194
	v_fmamk_f32 v141, v141, 0x3e0293ee, v194
	v_fmamk_f32 v142, v142, 0x3e0293ee, v194
	v_fmamk_f32 v143, v143, 0x3e0293ee, v194
	v_fmamk_f32 v144, v144, 0x3e0293ee, v194
	v_fmac_f32_e32 v194, 0x3e0293ee, v145
	v_exp_f32_e32 v145, v146
	v_exp_f32_e32 v146, v147
	v_exp_f32_e32 v147, v148
	v_exp_f32_e32 v148, v149
	v_exp_f32_e32 v149, v150
	v_exp_f32_e32 v150, v151
	v_exp_f32_e32 v151, v152
	v_exp_f32_e32 v152, v153
	v_exp_f32_e32 v153, v154
	v_exp_f32_e32 v154, v155
	v_exp_f32_e32 v155, v156
	v_exp_f32_e32 v156, v157
	v_exp_f32_e32 v157, v158
	v_exp_f32_e32 v158, v159
	v_exp_f32_e32 v159, v160
	v_exp_f32_e32 v160, v161
	v_exp_f32_e32 v161, v130
	v_add_f32_e32 v130, 0, v145
	v_add_f32_e32 v130, v146, v130
	v_add_f32_e32 v130, v147, v130
	v_add_f32_e32 v130, v148, v130
	v_add_f32_e32 v130, v149, v130
	v_add_f32_e32 v130, v150, v130
	v_add_f32_e32 v130, v151, v130
	v_add_f32_e32 v130, v152, v130
	v_add_f32_e32 v130, v153, v130
	v_add_f32_e32 v130, v154, v130
	v_add_f32_e32 v130, v155, v130
	v_add_f32_e32 v130, v156, v130
	v_add_f32_e32 v130, v157, v130
	v_exp_f32_e32 v195, v131
	v_add_f32_e32 v130, v158, v130
	v_exp_f32_e32 v196, v132
	v_add_f32_e32 v130, v159, v130
	v_exp_f32_e32 v197, v133
	v_add_f32_e32 v130, v160, v130
	v_exp_f32_e32 v198, v134
	v_add_f32_e32 v130, v161, v130
	v_exp_f32_e32 v199, v135
	v_add_f32_e32 v130, v195, v130
	v_exp_f32_e32 v200, v136
	v_add_f32_e32 v130, v196, v130
	v_exp_f32_e32 v201, v137
	v_add_f32_e32 v130, v197, v130
	v_exp_f32_e32 v202, v138
	v_add_f32_e32 v130, v198, v130
	v_exp_f32_e32 v203, v139
	v_add_f32_e32 v130, v199, v130
	v_exp_f32_e32 v204, v140
	v_add_f32_e32 v130, v200, v130
	v_exp_f32_e32 v205, v141
	v_add_f32_e32 v130, v201, v130
	v_exp_f32_e32 v206, v142
	v_add_f32_e32 v130, v202, v130
	v_exp_f32_e32 v207, v143
	v_add_f32_e32 v130, v203, v130
	v_exp_f32_e32 v208, v144
	v_add_f32_e32 v130, v204, v130
	v_exp_f32_e32 v194, v194
	v_add_f32_e32 v130, v205, v130
	v_add_f32_e32 v130, v206, v130
	v_add_f32_e32 v130, v207, v130
	v_add_f32_e32 v130, v208, v130
	v_add_f32_e32 v247, v194, v130
	v_mov_b32_e32 v248, v247
	s_nop 1
	v_permlane32_swap_b32_e32 v247, v248
	s_waitcnt vmcnt(0)
	s_barrier
	s_setprio 0
	v_cvt_pk_bf16_f32 v130, v145, v146
	v_cvt_pk_bf16_f32 v131, v147, v148
	v_cvt_pk_bf16_f32 v132, v149, v150
	v_cvt_pk_bf16_f32 v133, v151, v152
	v_cvt_pk_bf16_f32 v134, v153, v154
	v_cvt_pk_bf16_f32 v135, v155, v156
	v_cvt_pk_bf16_f32 v136, v157, v158
	v_cvt_pk_bf16_f32 v137, v159, v160
	v_cvt_pk_bf16_f32 v138, v161, v195
	v_cvt_pk_bf16_f32 v139, v196, v197
	v_cvt_pk_bf16_f32 v140, v198, v199
	v_cvt_pk_bf16_f32 v141, v200, v201
	v_cvt_pk_bf16_f32 v142, v202, v203
	v_cvt_pk_bf16_f32 v143, v204, v205
	v_cvt_pk_bf16_f32 v144, v206, v207
	v_cvt_pk_bf16_f32 v145, v208, v194
	s_nop 0
	v_permlane32_swap_b32_e32 v130, v132
	v_permlane32_swap_b32_e32 v131, v133
	v_permlane32_swap_b32_e32 v134, v136
	v_permlane32_swap_b32_e32 v135, v137
	v_permlane32_swap_b32_e32 v138, v140
	v_permlane32_swap_b32_e32 v139, v141
	v_permlane32_swap_b32_e32 v142, v144
	v_permlane32_swap_b32_e32 v143, v145
	s_waitcnt lgkmcnt(0)
	ds_read_b64_tr_b16 v[146:147], v213 offset:0
	ds_read_b64_tr_b16 v[148:149], v213 offset:2048
	ds_read_b64_tr_b16 v[150:151], v213 offset:4096
	ds_read_b64_tr_b16 v[152:153], v213 offset:6144
	ds_read_b64_tr_b16 v[154:155], v213 offset:8192
	ds_read_b64_tr_b16 v[156:157], v213 offset:10240
	ds_read_b64_tr_b16 v[158:159], v213 offset:12288
	ds_read_b64_tr_b16 v[160:161], v213 offset:14336
	v_lshl_add_u64 v[232:233], v[218:219], 0, s[22:23]
	v_lshl_add_u64 v[232:233], v[232:233], 0, s[10:11]
	s_add_i32 m0, s62, 0x8000
	s_nop 0
	global_load_lds_dwordx4 v[232:233], off
	s_waitcnt lgkmcnt(6)
	s_nop 0
	v_mfma_f32_32x32x16_bf16 v[114:129], v[130:133], v[146:149], v[114:129]
	ds_read_b64_tr_b16 v[146:147], v213 offset:512
	ds_read_b64_tr_b16 v[148:149], v213 offset:2560
	v_lshl_add_u64 v[232:233], v[218:219], 0, s[22:23]
	v_lshl_add_u64 v[232:233], v[232:233], 0, s[12:13]
	s_add_i32 m0, s62, 0xc000
	s_nop 0
	global_load_lds_dwordx4 v[232:233], off
	s_waitcnt lgkmcnt(6)
	v_mfma_f32_32x32x16_bf16 v[114:129], v[134:137], v[150:153], v[114:129]
	ds_read_b64_tr_b16 v[150:151], v213 offset:4608
	ds_read_b64_tr_b16 v[152:153], v213 offset:6656
	v_lshl_add_u64 v[232:233], v[220:221], 0, s[22:23]
	v_lshl_add_u64 v[232:233], v[232:233], 0, s[10:11]
	s_add_i32 m0, s62, 0x8400
	s_nop 0
	global_load_lds_dwordx4 v[232:233], off
	s_waitcnt lgkmcnt(6)
	v_mfma_f32_32x32x16_bf16 v[114:129], v[138:141], v[154:157], v[114:129]
	ds_read_b64_tr_b16 v[154:155], v213 offset:8704
	ds_read_b64_tr_b16 v[156:157], v213 offset:10752
	v_lshl_add_u64 v[232:233], v[220:221], 0, s[22:23]
	v_lshl_add_u64 v[232:233], v[232:233], 0, s[12:13]
	s_add_i32 m0, s62, 0xc400
	s_nop 0
	global_load_lds_dwordx4 v[232:233], off
	s_waitcnt lgkmcnt(6)
	v_mfma_f32_32x32x16_bf16 v[114:129], v[142:145], v[158:161], v[114:129]
	ds_read_b64_tr_b16 v[158:159], v213 offset:12800
	ds_read_b64_tr_b16 v[160:161], v213 offset:14848
	s_waitcnt lgkmcnt(6)
	v_mfma_f32_32x32x16_bf16 v[98:113], v[130:133], v[146:149], v[98:113]
	ds_read_b64_tr_b16 v[146:147], v213 offset:1024
	ds_read_b64_tr_b16 v[148:149], v213 offset:3072
	s_waitcnt lgkmcnt(6)
	v_mfma_f32_32x32x16_bf16 v[98:113], v[134:137], v[150:153], v[98:113]
	ds_read_b64_tr_b16 v[150:151], v213 offset:5120
	ds_read_b64_tr_b16 v[152:153], v213 offset:7168
	s_waitcnt lgkmcnt(6)
	v_mfma_f32_32x32x16_bf16 v[98:113], v[138:141], v[154:157], v[98:113]
	ds_read_b64_tr_b16 v[154:155], v213 offset:9216
	ds_read_b64_tr_b16 v[156:157], v213 offset:11264
	s_waitcnt lgkmcnt(6)
	v_mfma_f32_32x32x16_bf16 v[98:113], v[142:145], v[158:161], v[98:113]
	ds_read_b64_tr_b16 v[158:159], v213 offset:13312
	ds_read_b64_tr_b16 v[160:161], v213 offset:15360
	s_cmp_lt_u32 s29, 0x2000
	s_cbranch_scc1 .Lda_l1_s0_nolk
; #define SBAR() __builtin_amdgcn_sched_barrier(0)
; #define DPUB() do { asm volatile("s_waitcnt vmcnt(0)" ::: "memory"); __syncthreads(); } while (0)
; #define DTILE(b) do { f32x16 p0 = f32x16{}, p1 = f32x16{}; float mn, al; bf16x8 pa0, pa1, pa2, pa3; \
;     qkt_rolling<(b) * DA_KB>(p0, p1, ka0, qr); partialSM(p0, p1, m_reg, mn, al); DRESC(al); finishSM(p0, p1, al, l_reg, pa0, pa1, pa2, pa3); SBAR(); \
;     pv_all_rolling(o, vb0 + (b) * DA_VB, pa0, pa1, pa2, pa3); } while (0)
; template <int I> __device__ __forceinline__ void pv_rd(int vb, s16x4& l, s16x4& h) {
;   constexpr int D0 = I >> 2, KS = I & 3, IMG = (D0 >> 2) * 16384, DD = D0 & 3;
;   l = tr_read<IMG + v_rd_off(DD, KS, 0)>(vb); h = tr_read<IMG + v_rd_off(DD, KS, 1)>(vb);
; }
; template <int I> __device__ __forceinline__ void pv_step(f32x16* o, int vb, const bf16x8 (&pa)[4], s16x4 (&l)[3], s16x4 (&h)[3]) {
;   if constexpr (I + 2 < 32) pv_rd<(I + 2 < 32 ? I + 2 : 0)>(vb, l[(I + 2) % 3], h[(I + 2) % 3]);
;   if constexpr (I + 2 < 32) asm volatile("s_waitcnt lgkmcnt(4)" ::: "memory"); else if constexpr (I + 1 < 32) asm volatile("s_waitcnt lgkmcnt(2)" ::: "memory"); else asm volatile("s_waitcnt lgkmcnt(0)" ::: "memory");
;   SBAR();
;   const s16x4 L = l[I % 3], H = h[I % 3];
;   o[I >> 2] = __builtin_amdgcn_mfma_f32_32x32x16_bf16(pa[I & 3], (bf16x8){L[0], L[1], L[2], L[3], H[0], H[1], H[2], H[3]}, o[I >> 2], 0, 0, 0);
;   SBAR();
;   if constexpr (I + 1 < 32) pv_step<(I + 1 < 32 ? I + 1 : 31)>(o, vb, pa, l, h);
; }
; __device__ __forceinline__ void pv_all_rolling(f32x16* o, int vb, bf16x8 pa0, bf16x8 pa1, bf16x8 pa2, bf16x8 pa3) {
;   const bf16x8 pa[4] = {pa0, pa1, pa2, pa3}; s16x4 l[3], h[3];
;   asm volatile("s_waitcnt lgkmcnt(0)" ::: "memory");
;   pv_rd<0>(vb, l[0], h[0]); pv_rd<1>(vb, l[1], h[1]);
;   pv_step<0>(o, vb, pa, l, h);
; }
; __device__ __forceinline__ void unit_body_da(const Unit& U, char* lds) {
;     ...
;   for (int j = 0; j < NT; j += 2) {
;     DDMA(j + 1, 1); SBAR();
;     DTILE(0); SBAR(); DPUB();
;     if (j + 2 < NT) DDMA(j + 2, 0); SBAR();
;     DTILE(1); SBAR(); DPUB();
;   }
	v_lshl_add_u64 v[232:233], v[224:225], 0, s[14:15]
	s_mov_b32 m0, s61
	s_nop 0
	global_load_lds_dwordx4 v[232:233], off
	v_lshl_add_u64 v[232:233], v[228:229], 0, s[14:15]
	s_mov_b32 m0, s67
	s_nop 0
	global_load_lds_dwordx4 v[232:233], off
.Lda_l1_s0_nolk:
	s_waitcnt lgkmcnt(6)
	v_mfma_f32_32x32x16_bf16 v[82:97], v[130:133], v[146:149], v[82:97]
	ds_read_b64_tr_b16 v[146:147], v213 offset:1536
	ds_read_b64_tr_b16 v[148:149], v213 offset:3584
	s_waitcnt lgkmcnt(6)
	v_mfma_f32_32x32x16_bf16 v[82:97], v[134:137], v[150:153], v[82:97]
	ds_read_b64_tr_b16 v[150:151], v213 offset:5632
	ds_read_b64_tr_b16 v[152:153], v213 offset:7680
	s_waitcnt lgkmcnt(6)
	v_mfma_f32_32x32x16_bf16 v[82:97], v[138:141], v[154:157], v[82:97]
	ds_read_b64_tr_b16 v[154:155], v213 offset:9728
	ds_read_b64_tr_b16 v[156:157], v213 offset:11776
	s_waitcnt lgkmcnt(6)
	v_mfma_f32_32x32x16_bf16 v[82:97], v[142:145], v[158:161], v[82:97]
	ds_read_b64_tr_b16 v[158:159], v213 offset:13824
	ds_read_b64_tr_b16 v[160:161], v213 offset:15872
	s_waitcnt lgkmcnt(6)
	v_mfma_f32_32x32x16_bf16 v[66:81], v[130:133], v[146:149], v[66:81]
	ds_read_b64_tr_b16 v[146:147], v213 offset:16384
	ds_read_b64_tr_b16 v[148:149], v213 offset:18432
	s_waitcnt lgkmcnt(6)
	v_mfma_f32_32x32x16_bf16 v[66:81], v[134:137], v[150:153], v[66:81]
	ds_read_b64_tr_b16 v[150:151], v213 offset:20480
	ds_read_b64_tr_b16 v[152:153], v213 offset:22528
	s_waitcnt lgkmcnt(6)
	v_mfma_f32_32x32x16_bf16 v[66:81], v[138:141], v[154:157], v[66:81]
	ds_read_b64_tr_b16 v[154:155], v213 offset:24576
	ds_read_b64_tr_b16 v[156:157], v213 offset:26624
	s_waitcnt lgkmcnt(6)
	v_mfma_f32_32x32x16_bf16 v[66:81], v[142:145], v[158:161], v[66:81]
	ds_read_b64_tr_b16 v[158:159], v213 offset:28672
	ds_read_b64_tr_b16 v[160:161], v213 offset:30720
	s_waitcnt lgkmcnt(6)
	v_mfma_f32_32x32x16_bf16 v[50:65], v[130:133], v[146:149], v[50:65]
	ds_read_b64_tr_b16 v[146:147], v213 offset:16896
	ds_read_b64_tr_b16 v[148:149], v213 offset:18944
	s_waitcnt lgkmcnt(6)
	v_mfma_f32_32x32x16_bf16 v[50:65], v[134:137], v[150:153], v[50:65]
	ds_read_b64_tr_b16 v[150:151], v213 offset:20992
	ds_read_b64_tr_b16 v[152:153], v213 offset:23040
	s_waitcnt lgkmcnt(6)
	v_mfma_f32_32x32x16_bf16 v[50:65], v[138:141], v[154:157], v[50:65]
	ds_read_b64_tr_b16 v[154:155], v213 offset:25088
	ds_read_b64_tr_b16 v[156:157], v213 offset:27136
	s_waitcnt lgkmcnt(6)
	v_mfma_f32_32x32x16_bf16 v[50:65], v[142:145], v[158:161], v[50:65]
	ds_read_b64_tr_b16 v[158:159], v213 offset:29184
	ds_read_b64_tr_b16 v[160:161], v213 offset:31232
	s_waitcnt lgkmcnt(6)
	v_mfma_f32_32x32x16_bf16 v[34:49], v[130:133], v[146:149], v[34:49]
	ds_read_b64_tr_b16 v[146:147], v213 offset:17408
	ds_read_b64_tr_b16 v[148:149], v213 offset:19456
	s_waitcnt lgkmcnt(6)
	v_mfma_f32_32x32x16_bf16 v[34:49], v[134:137], v[150:153], v[34:49]
	ds_read_b64_tr_b16 v[150:151], v213 offset:21504
	ds_read_b64_tr_b16 v[152:153], v213 offset:23552
	s_waitcnt lgkmcnt(6)
	v_mfma_f32_32x32x16_bf16 v[34:49], v[138:141], v[154:157], v[34:49]
	ds_read_b64_tr_b16 v[154:155], v213 offset:25600
	ds_read_b64_tr_b16 v[156:157], v213 offset:27648
	s_waitcnt lgkmcnt(6)
	v_mfma_f32_32x32x16_bf16 v[34:49], v[142:145], v[158:161], v[34:49]
	ds_read_b64_tr_b16 v[158:159], v213 offset:29696
	ds_read_b64_tr_b16 v[160:161], v213 offset:31744
	s_waitcnt lgkmcnt(6)
	v_mfma_f32_32x32x16_bf16 v[18:33], v[130:133], v[146:149], v[18:33]
	ds_read_b64_tr_b16 v[146:147], v213 offset:17920
	ds_read_b64_tr_b16 v[148:149], v213 offset:19968
	s_waitcnt lgkmcnt(6)
	v_mfma_f32_32x32x16_bf16 v[18:33], v[134:137], v[150:153], v[18:33]
	ds_read_b64_tr_b16 v[150:151], v213 offset:22016
	ds_read_b64_tr_b16 v[152:153], v213 offset:24064
	s_waitcnt lgkmcnt(6)
	v_mfma_f32_32x32x16_bf16 v[18:33], v[138:141], v[154:157], v[18:33]
	ds_read_b64_tr_b16 v[154:155], v213 offset:26112
	ds_read_b64_tr_b16 v[156:157], v213 offset:28160
	s_waitcnt lgkmcnt(6)
	v_mfma_f32_32x32x16_bf16 v[18:33], v[142:145], v[158:161], v[18:33]
	ds_read_b64_tr_b16 v[158:159], v213 offset:30208
	ds_read_b64_tr_b16 v[160:161], v213 offset:32256
	ds_read_b128 v[194:197], v235 offset:16384
	ds_read_b128 v[198:201], v236 offset:16384
	ds_read_b128 v[202:205], v238 offset:16384
	ds_read_b128 v[206:209], v239 offset:16384
	s_waitcnt lgkmcnt(10)
	v_mfma_f32_32x32x16_bf16 v[2:17], v[130:133], v[146:149], v[2:17]
	s_waitcnt lgkmcnt(8)
	v_mfma_f32_32x32x16_bf16 v[2:17], v[134:137], v[150:153], v[2:17]
	s_waitcnt lgkmcnt(6)
	v_mfma_f32_32x32x16_bf16 v[2:17], v[138:141], v[154:157], v[2:17]
	s_waitcnt lgkmcnt(4)
	v_mfma_f32_32x32x16_bf16 v[2:17], v[142:145], v[158:161], v[2:17]
	s_waitcnt vmcnt(0)
	s_cmp_ge_u32 s80, s96
	s_cselect_b64 s[24:25], -1, 0
	s_and_b64 vcc, exec, s[24:25]
	s_waitcnt vmcnt(0) lgkmcnt(0)
	s_barrier
; #define SBAR() __builtin_amdgcn_sched_barrier(0)
; __device__ __forceinline__ void partialSM(f32x16& p0, f32x16& p1, float& m_reg, float& mn, float& alpha) {
;   constexpr float C = SCALE * 1.4426950408889634f;
;   float pmax = p0[0];
; #pragma unroll
;   for (int r = 1; r < 16; ++r) pmax = fmaxf(pmax, p0[r]);
; #pragma unroll
;   for (int r = 0; r < 16; ++r) pmax = fmaxf(pmax, p1[r]);
;   { auto rr = __builtin_amdgcn_permlane32_swap(__float_as_uint(pmax), __float_as_uint(pmax), false, false);
;     pmax = fmaxf(__uint_as_float(rr[0]), __uint_as_float(rr[1])); }
;   if (__builtin_expect(__all(pmax - m_reg <= THR / SCALE), 1)) { mn = m_reg; alpha = 1.f; }
; template <int OFF> __device__ __forceinline__ bf16x8 k_read(int a) { bf16x8 r; asm volatile("ds_read_b128 %0, %1 offset:%2" : "=&v"(r) : "v"(a), "i"(OFF) : "memory"); return r; }
; template <int BUFOFF, int D0> __device__ __forceinline__ void qk_step(f32x16& p0, f32x16& p1, int ka0, const bf16x8 (&qr)[8], bf16x8 (&k0)[2], bf16x8 (&k1)[2]) {
;   if constexpr (D0 + 1 < 8) { const int a_ = ka0 ^ ((D0 + 1) << 5); k0[(D0 + 1) & 1] = k_read<BUFOFF>(a_); k1[(D0 + 1) & 1] = k_read<BUFOFF + 8192>(a_); }
;   if constexpr (D0 + 1 < 8) asm volatile("s_waitcnt lgkmcnt(2)" ::: "memory"); else asm volatile("s_waitcnt lgkmcnt(0)" ::: "memory");
;   SBAR();
;   p0 = __builtin_amdgcn_mfma_f32_32x32x16_bf16(k0[D0 & 1], qr[D0], p0, 0, 0, 0);
;   p1 = __builtin_amdgcn_mfma_f32_32x32x16_bf16(k1[D0 & 1], qr[D0], p1, 0, 0, 0);
;   SBAR();
;   if constexpr (D0 + 1 < 8) qk_step<BUFOFF, (D0 + 1 < 8 ? D0 + 1 : 7)>(p0, p1, ka0, qr, k0, k1);
; }
; template <int BUFOFF> __device__ __forceinline__ void qkt_rolling(f32x16& p0, f32x16& p1, int ka0, const bf16x8 (&qr)[8]) {
;   bf16x8 k0[2], k1[2];
;   asm volatile("s_waitcnt lgkmcnt(0)" ::: "memory");
;   k0[0] = k_read<BUFOFF>(ka0); k1[0] = k_read<BUFOFF + 8192>(ka0);
;   qk_step<BUFOFF, 0>(p0, p1, ka0, qr, k0, k1);
; }
.LBB0_1442:
	s_setprio 1
	s_waitcnt lgkmcnt(0)
	ds_read_b128 v[130:133], v240 offset:16384
	ds_read_b128 v[134:137], v241 offset:16384
	ds_read_b128 v[138:141], v242 offset:16384
	ds_read_b128 v[142:145], v243 offset:16384
	s_cmp_lt_u32 s29, 0x2000
	s_cbranch_scc0 .Lda_l1_s1_nok
	v_lshl_add_u64 v[232:233], v[224:225], 0, s[14:15]
	s_mov_b32 m0, s61
	s_nop 0
	global_load_lds_dwordx4 v[232:233], off
	v_lshl_add_u64 v[232:233], v[228:229], 0, s[14:15]
	s_mov_b32 m0, s67
	s_nop 0
	global_load_lds_dwordx4 v[232:233], off
.Lda_l1_s1_nok:
	s_waitcnt lgkmcnt(7)
	s_nop 0
	v_mfma_f32_32x32x16_bf16 v[146:161], v[194:197], v[162:165], 0
	ds_read_b128 v[194:197], v235 offset:24576
	s_waitcnt lgkmcnt(7)
	v_mfma_f32_32x32x16_bf16 v[146:161], v[198:201], v[166:169], v[146:161]
	ds_read_b128 v[198:201], v236 offset:24576
	s_waitcnt lgkmcnt(7)
	v_mfma_f32_32x32x16_bf16 v[146:161], v[202:205], v[170:173], v[146:161]
	ds_read_b128 v[202:205], v238 offset:24576
	s_waitcnt lgkmcnt(7)
	v_mfma_f32_32x32x16_bf16 v[146:161], v[206:209], v[174:177], v[146:161]
	ds_read_b128 v[206:209], v239 offset:24576
	s_waitcnt lgkmcnt(7)
	v_mfma_f32_32x32x16_bf16 v[146:161], v[130:133], v[178:181], v[146:161]
	s_waitcnt lgkmcnt(6)
	v_mfma_f32_32x32x16_bf16 v[146:161], v[134:137], v[182:185], v[146:161]
	s_waitcnt lgkmcnt(5)
	v_mfma_f32_32x32x16_bf16 v[146:161], v[138:141], v[186:189], v[146:161]
	s_waitcnt lgkmcnt(4)
	v_mfma_f32_32x32x16_bf16 v[146:161], v[142:145], v[190:193], v[146:161]
	s_waitcnt lgkmcnt(3)
	v_mfma_f32_32x32x16_bf16 v[130:145], v[194:197], v[162:165], 0
	ds_read_b128 v[194:197], v240 offset:24576
	s_waitcnt lgkmcnt(3)
	v_mfma_f32_32x32x16_bf16 v[130:145], v[198:201], v[166:169], v[130:145]
	ds_read_b128 v[198:201], v241 offset:24576
	s_waitcnt lgkmcnt(3)
	v_mfma_f32_32x32x16_bf16 v[130:145], v[202:205], v[170:173], v[130:145]
	ds_read_b128 v[202:205], v242 offset:24576
	s_waitcnt lgkmcnt(3)
	v_mfma_f32_32x32x16_bf16 v[130:145], v[206:209], v[174:177], v[130:145]
	ds_read_b128 v[206:209], v243 offset:24576
	s_waitcnt lgkmcnt(3)
	v_mfma_f32_32x32x16_bf16 v[130:145], v[194:197], v[178:181], v[130:145]
	s_waitcnt lgkmcnt(2)
	v_mfma_f32_32x32x16_bf16 v[130:145], v[198:201], v[182:185], v[130:145]
	s_waitcnt lgkmcnt(1)
	v_mfma_f32_32x32x16_bf16 v[130:145], v[202:205], v[186:189], v[130:145]
	s_waitcnt lgkmcnt(0)
	v_mfma_f32_32x32x16_bf16 v[130:145], v[206:209], v[190:193], v[130:145]
	s_setprio 0
	v_max3_f32 v194, v146, v147, v148
	v_max3_f32 v195, v154, v155, v156
	v_max3_f32 v194, v194, v149, v150
	v_max3_f32 v195, v195, v157, v158
	v_max3_f32 v194, v194, v151, v152
	v_max3_f32 v195, v195, v159, v160
	v_max_f32_e32 v194, v194, v153
	v_max_f32_e32 v195, v195, v161
	s_nop 4
	v_max3_f32 v196, v130, v131, v132
	v_max3_f32 v197, v138, v139, v140
	v_max3_f32 v196, v196, v133, v134
	v_max3_f32 v197, v197, v141, v142
	v_max3_f32 v196, v196, v135, v136
	v_max3_f32 v197, v197, v143, v144
	v_max_f32_e32 v196, v196, v137
	v_max_f32_e32 v197, v197, v145
	v_max3_f32 v194, v194, v195, v196
	v_max_f32_e32 v194, v194, v197
	v_mov_b32_e32 v195, v194
	s_nop 1
	v_permlane32_swap_b32_e32 v194, v195
	v_max_f32_e32 v194, v194, v195
	v_sub_f32_e32 v195, v194, v246
	v_cmp_ge_f32_e32 vcc, s95, v195
	s_cmp_eq_u64 vcc, exec
	s_cbranch_scc0 .Lda_slow_l1_2
	s_mov_b64 s[6:7], -1
	v_mov_b32_e32 v222, 1.0
	s_branch .LBB0_1435
